# strategy 7.4: one static s_setprio 1 for waves 0-3 at kernel entry, all 56 per-segment flips deleted (on v028)
# baseline (speedup 1.0000x reference)
; #define LAS __attribute__((address_space(3)))
; DI unsigned xb_add(unsigned* p, unsigned v) { return __hip_atomic_fetch_add(p, v, __ATOMIC_RELAXED, __HIP_MEMORY_SCOPE_AGENT); }
; DI unsigned xb_xcc_id() { return (unsigned)__builtin_amdgcn_s_getreg((3 << 11) | 20) & 0xFu; }
; DI XcdBarrier xcd_barrier_post(unsigned* bar, volatile LAS unsigned* st) {
;     XcdBarrier b; b.bar = bar; b.x = xb_xcc_id(); b.st = st;
;     if (threadIdx.x == 0) st[2] = xb_add(&bar[XB_XCNT(b.x)], 1u);
;     return b;
; __global__ void __launch_bounds__(NTHREADS, 2) mega_fwd(Args a) {
;     extern __shared__ __attribute__((aligned(16))) unsigned char lds_raw[];
;     LAS unsigned char* lds = (LAS unsigned char*)lds_raw;
;     const int G = gridDim.x, bid = blockIdx.x, ngw = G * NWAVES;
;     int cv = bid; bool grouped = false;
;     unsigned char* ws = a.ws;
;     bf16_t* XB = (bf16_t*)(ws + WS_XB); float* Y = (float*)(ws + WS_Y); bf16_t* BIG = (bf16_t*)(ws + WS_BIG);
;     bf16_t* DP = (bf16_t*)(ws + WS_DP); bf16_t* CAT = (bf16_t*)(ws + WS_CAT); bf16_t* VT = (bf16_t*)(ws + WS_VT);
;     float* X = a.out;
;     volatile LAS unsigned* misc = (volatile LAS unsigned*)(lds + MISC_OFF);
;     if (threadIdx.x < 16) misc[threadIdx.x] = 0u;
;     __syncthreads();
;     XcdBarrier xbar; xbar.bar = (unsigned*)(ws + WS_CTL); xbar.x = 0; xbar.st = misc;
;     if (a.ph_hi - a.ph_lo > 1) xbar = xcd_barrier_post((unsigned*)(ws + WS_CTL), misc);
_Z8mega_fwd4Args:
	v_readfirstlane_b32 s100, v0
	s_nop 3
	s_and_b32 s100, s100, 0x3ff
	s_lshr_b32 s100, s100, 6
	s_cmp_ge_u32 s100, 4
	s_cbranch_scc1 .Lprio_done
	s_setprio 1
.Lprio_done:
	s_load_dwordx8 s[88:95], s[0:1], 0x60
	s_load_dwordx8 s[4:11], s[0:1], 0x40
	v_and_b32_e32 v188, 0x3ff, v0
	v_cmp_gt_u32_e32 vcc, 16, v188
	s_waitcnt lgkmcnt(0)
	v_writelane_b32 v253, s4, 0
	s_nop 1
	v_writelane_b32 v253, s5, 1
	v_writelane_b32 v253, s6, 2
	v_writelane_b32 v253, s7, 3
	v_writelane_b32 v253, s8, 4
	v_writelane_b32 v253, s9, 5
	v_writelane_b32 v253, s10, 6
	v_writelane_b32 v253, s11, 7
	s_load_dword s10, s[0:1], 0x80
	s_add_u32 s4, s0, 0x80
	s_addc_u32 s5, s1, 0
	v_writelane_b32 v253, s4, 8
	s_nop 1
	v_writelane_b32 v253, s5, 9
	s_and_saveexec_b64 s[12:13], vcc
	v_lshl_add_u32 v1, v188, 2, 0
	v_add_u32_e32 v1, 0x23fc0, v1
	v_mov_b32_e32 v2, 0
	ds_write_b32 v1, v2
	s_or_b64 exec, exec, s[12:13]
	s_add_u32 s18, s92, 0x23080000
	s_addc_u32 s19, s93, 0
	s_sub_i32 s3, s95, s94
	s_mov_b32 s4, 0
	s_cmp_gt_i32 s3, 1
	v_writelane_b32 v253, s4, 10
	s_cselect_b64 s[16:17], -1, 0
	s_cmp_lt_i32 s3, 2
	v_cmp_eq_u32_e32 vcc, 0, v188
	s_waitcnt lgkmcnt(0)
	s_barrier
	s_cbranch_scc1 .LBB0_8
	s_getreg_b32 s3, hwreg(HW_REG_XCC_ID, 0, 4)
	s_and_b32 s3, s3, 15
	v_writelane_b32 v253, s3, 10
	s_and_saveexec_b64 s[12:13], vcc
	s_cbranch_execz .LBB0_7
	s_mov_b64 s[20:21], exec
	v_mbcnt_lo_u32_b32 v1, s20, 0
	v_mbcnt_hi_u32_b32 v1, s21, v1
	v_cmp_eq_u32_e32 vcc, 0, v1
	s_and_saveexec_b64 s[14:15], vcc
	s_cbranch_execz .LBB0_6
	v_readlane_b32 s3, v253, 10
	s_lshl_b32 s3, s3, 8
	s_bcnt1_i32_b64 s4, s[20:21]
	v_mov_b32_e32 v2, s3
	v_mov_b32_e32 v3, s4
	global_atomic_add v2, v2, v3, s[18:19] offset:1024 sc0

; #define PG8_STAGE(bufoff, gbase, voff) do { _Pragma("unroll") for (int _i = 0; _i < 2; ++_i) \
;         __builtin_amdgcn_global_load_lds((const unsigned*)((const char*)(gbase) + (voff)[_i]), (LAS unsigned*)(lds + (bufoff) + ldsw + _i * 8192), 16, 0, 0); } while (0)
; #define PG8_LDA(dst, b, h) do { _Pragma("unroll") for (int m = 0; m < 4; ++m) _Pragma("unroll") for (int k = 0; k < 2; ++k) dst[m][k] = *(const LAS bf16x8*)(lds + PG8_SA(b, h) + aoff + m * 2048 + k * 1024); } while (0)
; #define PG8_LDB(dst, b, h) do { _Pragma("unroll") for (int n = 0; n < 2; ++n) _Pragma("unroll") for (int k = 0; k < 2; ++k) dst[n][k] = *(const LAS bf16x8*)(lds + PG8_SB(b, h) + boff + n * 2048 + k * 1024); } while (0)
; #define PG8_MMA(ai, bj, At, Bt) do { __builtin_amdgcn_s_setprio(1); _Pragma("unroll") for (int m = 0; m < 4; ++m) _Pragma("unroll") for (int n = 0; n < 2; ++n) _Pragma("unroll") for (int k = 0; k < 2; ++k) \
;         acc[ai][bj][m][n] = __builtin_amdgcn_mfma_f32_16x16x32_bf16(Bt[n][k], At[m][k], acc[ai][bj][m][n], 0, 0, 0); __builtin_amdgcn_s_setprio(0); } while (0)
; #define PG8_WAIT_V(n) asm volatile("s_waitcnt vmcnt(" #n ")" ::: "memory")
; #define PG8_WAIT_L(n) asm volatile("s_waitcnt lgkmcnt(" #n ")" ::: "memory")
; #define PG8_BAR __builtin_amdgcn_s_barrier()
; #define PG8_SCHED __builtin_amdgcn_sched_barrier(0)
; template <class Epi, bool ALIGN_EPI, bool SP2, bool ROWHALF = false>
; DI void gemm_phase(LAS unsigned char* lds, const Gemm g, const StaticOrder& S, const Epi& E) {
;     ...
;         for (int t = 0; t < nt; t += 2) {
;             const bool last = (t == nt - 2);
;             const char* a1 = cA + (size_t)(t + 1) * kstep;
;             const char* a2 = last ? nA : cA + (size_t)(t + 2) * kstep; const char* b2 = last ? nB : cB + (size_t)(t + 2) * kstep;
;             const char* a3 = a2 + kstep; const char* b3 = b2 + kstep;
;             if constexpr (SP2) {
;             PG8_LDB(B0, 0, 0); PG8_LDB(B1, 0, 1); PG8_SCHED; PG8_LDA(At, 0, 0); PG8_STAGE(PG8_SA(1, 1), a1 + hA1, voffA);
;             PG8_WAIT_V(8); PG8_WAIT_L(0); PG8_BAR; PG8_MMA(0, 0, At, B0); PG8_MMA(0, 1, At, B1); PG8_BAR; PG8_SCHED;
;             if constexpr (!ROWHALF) { PG8_LDA(At, 0, 1); } PG8_STAGE(PG8_SB(0, 0), b2, voffB); PG8_STAGE(PG8_SB(0, 1), b2 + hstepB, voffB); PG8_STAGE(PG8_SA(0, 0), a2 + hA0, voffA);
.LBB0_122:
	s_add_i32 s81, s78, 2
	s_add_u32 s36, s76, 0x80
	s_addc_u32 s37, s77, 0
	s_add_i32 s82, 0, 0x10000
	s_cmp_eq_u32 s13, s78
	s_cselect_b32 s79, s1, s37
	s_cselect_b32 s78, s0, s36
	v_add_u32_e32 v144, s82, v147
	s_cselect_b32 s37, s75, s21
	s_cselect_b32 s36, s74, s20
	s_add_i32 s83, 0, 0x14000
	ds_read_b128 v[130:133], v144
	ds_read_b128 v[150:153], v144 offset:1024
	ds_read_b128 v[154:157], v144 offset:2048
	ds_read_b128 v[158:161], v144 offset:3072
	v_add_u32_e32 v144, s83, v147
	ds_read_b128 v[164:167], v144
	ds_read_b128 v[168:171], v144 offset:1024
	ds_read_b128 v[172:175], v144 offset:2048
	ds_read_b128 v[176:179], v144 offset:3072
	v_lshl_add_u64 v[144:145], s[76:77], 0, v[140:141]
	s_add_i32 m0, s7, 0xc000
	ds_read_b128 v[180:183], v149
	ds_read_b128 v[184:187], v149 offset:1024
	ds_read_b128 v[216:219], v149 offset:2048
	ds_read_b128 v[220:223], v149 offset:3072
	ds_read_b128 v[224:227], v149 offset:4096
	ds_read_b128 v[228:231], v149 offset:5120
	ds_read_b128 v[232:235], v149 offset:6144
	ds_read_b128 v[236:239], v149 offset:7168
	global_load_lds_dwordx4 v[144:145], off
	v_lshl_add_u64 v[144:145], s[76:77], 0, v[142:143]
	s_add_i32 m0, s7, 0xe000
	s_nop 0
	global_load_lds_dwordx4 v[144:145], off
	s_waitcnt vmcnt(8)
	s_waitcnt lgkmcnt(0)
	v_mfma_f32_16x16x32_bf16 v[118:121], v[130:133], v[180:183], v[118:121]
	v_mfma_f32_16x16x32_bf16 v[126:129], v[154:157], v[180:183], v[126:129]
	v_mfma_f32_16x16x32_bf16 v[110:113], v[130:133], v[216:219], v[110:113]
	v_mfma_f32_16x16x32_bf16 v[106:109], v[154:157], v[216:219], v[106:109]
	s_barrier
	v_mfma_f32_16x16x32_bf16 v[92:95], v[130:133], v[224:227], v[92:95]
	v_mfma_f32_16x16x32_bf16 v[88:91], v[154:157], v[224:227], v[88:91]
	v_mfma_f32_16x16x32_bf16 v[76:79], v[130:133], v[232:235], v[76:79]
	v_mfma_f32_16x16x32_bf16 v[72:75], v[154:157], v[232:235], v[72:75]
	v_mfma_f32_16x16x32_bf16 v[118:121], v[150:153], v[184:187], v[118:121]
	v_mfma_f32_16x16x32_bf16 v[126:129], v[158:161], v[184:187], v[126:129]
	v_mfma_f32_16x16x32_bf16 v[110:113], v[150:153], v[220:223], v[110:113]
	v_mfma_f32_16x16x32_bf16 v[106:109], v[158:161], v[220:223], v[106:109]
	v_mfma_f32_16x16x32_bf16 v[92:95], v[150:153], v[228:231], v[92:95]
	v_mfma_f32_16x16x32_bf16 v[88:91], v[158:161], v[228:231], v[88:91]
	v_mfma_f32_16x16x32_bf16 v[76:79], v[150:153], v[236:239], v[76:79]
	v_mfma_f32_16x16x32_bf16 v[72:75], v[158:161], v[236:239], v[72:75]
	v_mfma_f32_16x16x32_bf16 v[122:125], v[164:167], v[180:183], v[122:125]
	v_mfma_f32_16x16x32_bf16 v[114:117], v[172:175], v[180:183], v[114:117]
	v_mfma_f32_16x16x32_bf16 v[102:105], v[164:167], v[216:219], v[102:105]
	v_mfma_f32_16x16x32_bf16 v[98:101], v[172:175], v[216:219], v[98:101]
	v_mfma_f32_16x16x32_bf16 v[84:87], v[164:167], v[224:227], v[84:87]
	v_mfma_f32_16x16x32_bf16 v[80:83], v[172:175], v[224:227], v[80:83]
	v_mfma_f32_16x16x32_bf16 v[68:71], v[164:167], v[232:235], v[68:71]
	v_mfma_f32_16x16x32_bf16 v[64:67], v[172:175], v[232:235], v[64:67]
	v_mfma_f32_16x16x32_bf16 v[122:125], v[168:171], v[184:187], v[122:125]
	v_mfma_f32_16x16x32_bf16 v[114:117], v[176:179], v[184:187], v[114:117]
	v_mfma_f32_16x16x32_bf16 v[102:105], v[168:171], v[220:223], v[102:105]
	v_mfma_f32_16x16x32_bf16 v[98:101], v[176:179], v[220:223], v[98:101]
	v_mfma_f32_16x16x32_bf16 v[84:87], v[168:171], v[228:231], v[84:87]
	v_mfma_f32_16x16x32_bf16 v[80:83], v[176:179], v[228:231], v[80:83]
	v_mfma_f32_16x16x32_bf16 v[68:71], v[168:171], v[236:239], v[68:71]
	v_mfma_f32_16x16x32_bf16 v[64:67], v[176:179], v[236:239], v[64:67]
	s_barrier
	s_add_i32 s82, s82, s4
	v_lshl_add_u64 v[144:145], s[36:37], 0, v[96:97]
	s_mov_b32 m0, s82
	ds_read_b128 v[180:183], v149 offset:16384
	ds_read_b128 v[184:187], v149 offset:17408
	ds_read_b128 v[216:219], v149 offset:18432
	ds_read_b128 v[220:223], v149 offset:19456
	ds_read_b128 v[224:227], v149 offset:20480
	ds_read_b128 v[228:231], v149 offset:21504
	ds_read_b128 v[232:235], v149 offset:22528
	ds_read_b128 v[236:239], v149 offset:23552
	global_load_lds_dwordx4 v[144:145], off
	s_add_i32 m0, s82, 0x2000
	v_lshl_add_u64 v[192:193], s[36:37], 0, v[134:135]
	s_add_u32 s36, s36, s28
	s_addc_u32 s37, s37, 0
	s_add_i32 s82, s83, s4
	global_load_lds_dwordx4 v[192:193], off
	v_lshl_add_u64 v[194:195], s[36:37], 0, v[96:97]
	s_mov_b32 m0, s82
	v_lshl_add_u64 v[240:241], s[36:37], 0, v[134:135]
	global_load_lds_dwordx4 v[194:195], off
	s_add_i32 m0, s82, 0x2000
	v_lshl_add_u64 v[242:243], s[78:79], 0, v[138:139]
	global_load_lds_dwordx4 v[240:241], off
	s_mov_b32 m0, s7
	v_lshl_add_u64 v[244:245], s[78:79], 0, v[136:137]
	global_load_lds_dwordx4 v[242:243], off
	s_mov_b32 m0, s8
	s_nop 0
	global_load_lds_dwordx4 v[244:245], off
	s_waitcnt vmcnt(8)
	s_waitcnt lgkmcnt(0)
	v_mfma_f32_16x16x32_bf16 v[60:63], v[130:133], v[180:183], v[60:63]
	v_mfma_f32_16x16x32_bf16 v[56:59], v[154:157], v[180:183], v[56:59]
	v_mfma_f32_16x16x32_bf16 v[44:47], v[130:133], v[216:219], v[44:47]
	v_mfma_f32_16x16x32_bf16 v[40:43], v[154:157], v[216:219], v[40:43]
	s_barrier
; #define PG8_STAGE(bufoff, gbase, voff) do { _Pragma("unroll") for (int _i = 0; _i < 2; ++_i) \
;         __builtin_amdgcn_global_load_lds((const unsigned*)((const char*)(gbase) + (voff)[_i]), (LAS unsigned*)(lds + (bufoff) + ldsw + _i * 8192), 16, 0, 0); } while (0)
; #define PG8_LDA(dst, b, h) do { _Pragma("unroll") for (int m = 0; m < 4; ++m) _Pragma("unroll") for (int k = 0; k < 2; ++k) dst[m][k] = *(const LAS bf16x8*)(lds + PG8_SA(b, h) + aoff + m * 2048 + k * 1024); } while (0)
; #define PG8_LDB(dst, b, h) do { _Pragma("unroll") for (int n = 0; n < 2; ++n) _Pragma("unroll") for (int k = 0; k < 2; ++k) dst[n][k] = *(const LAS bf16x8*)(lds + PG8_SB(b, h) + boff + n * 2048 + k * 1024); } while (0)
; #define PG8_MMA(ai, bj, At, Bt) do { __builtin_amdgcn_s_setprio(1); _Pragma("unroll") for (int m = 0; m < 4; ++m) _Pragma("unroll") for (int n = 0; n < 2; ++n) _Pragma("unroll") for (int k = 0; k < 2; ++k) \
;         acc[ai][bj][m][n] = __builtin_amdgcn_mfma_f32_16x16x32_bf16(Bt[n][k], At[m][k], acc[ai][bj][m][n], 0, 0, 0); __builtin_amdgcn_s_setprio(0); } while (0)
; #define PG8_WAIT_V(n) asm volatile("s_waitcnt vmcnt(" #n ")" ::: "memory")
; #define PG8_WAIT_L(n) asm volatile("s_waitcnt lgkmcnt(" #n ")" ::: "memory")
; #define PG8_BAR __builtin_amdgcn_s_barrier()
; #define PG8_SCHED __builtin_amdgcn_sched_barrier(0)
; template <class Epi, bool ALIGN_EPI, bool SP2, bool ROWHALF = false>
; DI void gemm_phase(LAS unsigned char* lds, const Gemm g, const StaticOrder& S, const Epi& E) {
;     ...
;             PG8_WAIT_V(8); PG8_WAIT_L(0); PG8_BAR; if constexpr (!ROWHALF) { PG8_MMA(1, 0, At, B0); PG8_MMA(1, 1, At, B1); } PG8_BAR; PG8_SCHED;
;             PG8_LDB(B0, 1, 0); PG8_LDB(B1, 1, 1); PG8_SCHED; PG8_LDA(At, 1, 0); PG8_STAGE(PG8_SA(0, 1), a2 + hA1, voffA);
;             PG8_WAIT_V(8); PG8_WAIT_L(0); PG8_BAR; PG8_MMA(0, 0, At, B0); PG8_MMA(0, 1, At, B1); PG8_BAR; PG8_SCHED;
	v_mfma_f32_16x16x32_bf16 v[28:31], v[130:133], v[224:227], v[28:31]
	v_mfma_f32_16x16x32_bf16 v[24:27], v[154:157], v[224:227], v[24:27]
	v_mfma_f32_16x16x32_bf16 v[12:15], v[130:133], v[232:235], v[12:15]
	v_mfma_f32_16x16x32_bf16 v[8:11], v[154:157], v[232:235], v[8:11]
	v_mfma_f32_16x16x32_bf16 v[60:63], v[150:153], v[184:187], v[60:63]
	v_mfma_f32_16x16x32_bf16 v[56:59], v[158:161], v[184:187], v[56:59]
	v_mfma_f32_16x16x32_bf16 v[44:47], v[150:153], v[220:223], v[44:47]
	v_mfma_f32_16x16x32_bf16 v[40:43], v[158:161], v[220:223], v[40:43]
	v_mfma_f32_16x16x32_bf16 v[28:31], v[150:153], v[228:231], v[28:31]
	v_mfma_f32_16x16x32_bf16 v[24:27], v[158:161], v[228:231], v[24:27]
	v_mfma_f32_16x16x32_bf16 v[12:15], v[150:153], v[236:239], v[12:15]
	v_mfma_f32_16x16x32_bf16 v[8:11], v[158:161], v[236:239], v[8:11]
	v_mfma_f32_16x16x32_bf16 v[52:55], v[164:167], v[180:183], v[52:55]
	v_mfma_f32_16x16x32_bf16 v[48:51], v[172:175], v[180:183], v[48:51]
	v_mfma_f32_16x16x32_bf16 v[36:39], v[164:167], v[216:219], v[36:39]
	v_mfma_f32_16x16x32_bf16 v[32:35], v[172:175], v[216:219], v[32:35]
	v_mfma_f32_16x16x32_bf16 v[20:23], v[164:167], v[224:227], v[20:23]
	v_mfma_f32_16x16x32_bf16 v[16:19], v[172:175], v[224:227], v[16:19]
	v_mfma_f32_16x16x32_bf16 v[4:7], v[164:167], v[232:235], v[4:7]
	v_mfma_f32_16x16x32_bf16 v[0:3], v[172:175], v[232:235], v[0:3]
	v_mfma_f32_16x16x32_bf16 v[52:55], v[168:171], v[184:187], v[52:55]
	v_mfma_f32_16x16x32_bf16 v[48:51], v[176:179], v[184:187], v[48:51]
	v_mfma_f32_16x16x32_bf16 v[36:39], v[168:171], v[220:223], v[36:39]
	v_mfma_f32_16x16x32_bf16 v[32:35], v[176:179], v[220:223], v[32:35]
	v_mfma_f32_16x16x32_bf16 v[20:23], v[168:171], v[228:231], v[20:23]
	v_mfma_f32_16x16x32_bf16 v[16:19], v[176:179], v[228:231], v[16:19]
	v_mfma_f32_16x16x32_bf16 v[4:7], v[168:171], v[236:239], v[4:7]
	v_mfma_f32_16x16x32_bf16 v[0:3], v[176:179], v[236:239], v[0:3]
	s_barrier
	s_add_i32 s82, 0, 0x18000
	s_add_i32 s83, 0, 0x1c000
	v_add_u32_e32 v158, s82, v147
	v_add_u32_e32 v176, s83, v147
	ds_read_b128 v[130:133], v158
	ds_read_b128 v[150:153], v158 offset:1024
	ds_read_b128 v[154:157], v158 offset:2048
	ds_read_b128 v[158:161], v158 offset:3072
	ds_read_b128 v[164:167], v176
	ds_read_b128 v[168:171], v176 offset:1024
	ds_read_b128 v[172:175], v176 offset:2048
	ds_read_b128 v[176:179], v176 offset:3072
	s_add_u32 s36, s78, s18
	s_addc_u32 s37, s79, 0
	s_mov_b32 m0, s9
	v_lshl_add_u64 v[246:247], s[36:37], 0, v[138:139]
	ds_read_b128 v[180:183], v149 offset:32768
	ds_read_b128 v[184:187], v149 offset:33792
	ds_read_b128 v[216:219], v149 offset:34816
	ds_read_b128 v[220:223], v149 offset:35840
	ds_read_b128 v[224:227], v149 offset:36864
	ds_read_b128 v[228:231], v149 offset:37888
	ds_read_b128 v[232:235], v149 offset:38912
	ds_read_b128 v[236:239], v149 offset:39936
	global_load_lds_dwordx4 v[246:247], off
	v_lshl_add_u64 v[246:247], s[36:37], 0, v[136:137]
	s_mov_b32 m0, s10
	s_nop 0
	global_load_lds_dwordx4 v[246:247], off
	s_waitcnt vmcnt(8)
	s_waitcnt lgkmcnt(0)
	v_mfma_f32_16x16x32_bf16 v[118:121], v[130:133], v[180:183], v[118:121]
	v_mfma_f32_16x16x32_bf16 v[126:129], v[154:157], v[180:183], v[126:129]
	v_mfma_f32_16x16x32_bf16 v[110:113], v[130:133], v[216:219], v[110:113]
	v_mfma_f32_16x16x32_bf16 v[106:109], v[154:157], v[216:219], v[106:109]
	s_barrier
	v_mfma_f32_16x16x32_bf16 v[92:95], v[130:133], v[224:227], v[92:95]
	v_mfma_f32_16x16x32_bf16 v[88:91], v[154:157], v[224:227], v[88:91]
	v_mfma_f32_16x16x32_bf16 v[76:79], v[130:133], v[232:235], v[76:79]
	v_mfma_f32_16x16x32_bf16 v[72:75], v[154:157], v[232:235], v[72:75]
	v_mfma_f32_16x16x32_bf16 v[118:121], v[150:153], v[184:187], v[118:121]
	v_mfma_f32_16x16x32_bf16 v[126:129], v[158:161], v[184:187], v[126:129]
	v_mfma_f32_16x16x32_bf16 v[110:113], v[150:153], v[220:223], v[110:113]
	v_mfma_f32_16x16x32_bf16 v[106:109], v[158:161], v[220:223], v[106:109]
	v_mfma_f32_16x16x32_bf16 v[92:95], v[150:153], v[228:231], v[92:95]
	v_mfma_f32_16x16x32_bf16 v[88:91], v[158:161], v[228:231], v[88:91]
	v_mfma_f32_16x16x32_bf16 v[76:79], v[150:153], v[236:239], v[76:79]
	v_mfma_f32_16x16x32_bf16 v[72:75], v[158:161], v[236:239], v[72:75]
	v_mfma_f32_16x16x32_bf16 v[122:125], v[164:167], v[180:183], v[122:125]
	v_mfma_f32_16x16x32_bf16 v[114:117], v[172:175], v[180:183], v[114:117]
	v_mfma_f32_16x16x32_bf16 v[102:105], v[164:167], v[216:219], v[102:105]
	v_mfma_f32_16x16x32_bf16 v[98:101], v[172:175], v[216:219], v[98:101]
	v_mfma_f32_16x16x32_bf16 v[84:87], v[164:167], v[224:227], v[84:87]
	v_mfma_f32_16x16x32_bf16 v[80:83], v[172:175], v[224:227], v[80:83]
	v_mfma_f32_16x16x32_bf16 v[68:71], v[164:167], v[232:235], v[68:71]
	v_mfma_f32_16x16x32_bf16 v[64:67], v[172:175], v[232:235], v[64:67]
	v_mfma_f32_16x16x32_bf16 v[122:125], v[168:171], v[184:187], v[122:125]
	v_mfma_f32_16x16x32_bf16 v[114:117], v[176:179], v[184:187], v[114:117]
	v_mfma_f32_16x16x32_bf16 v[102:105], v[168:171], v[220:223], v[102:105]
	v_mfma_f32_16x16x32_bf16 v[98:101], v[176:179], v[220:223], v[98:101]
	v_mfma_f32_16x16x32_bf16 v[84:87], v[168:171], v[228:231], v[84:87]
	v_mfma_f32_16x16x32_bf16 v[80:83], v[176:179], v[228:231], v[80:83]
	v_mfma_f32_16x16x32_bf16 v[68:71], v[168:171], v[236:239], v[68:71]
	v_mfma_f32_16x16x32_bf16 v[64:67], v[176:179], v[236:239], v[64:67]
	s_barrier
; #define PG8_STAGE(bufoff, gbase, voff) do { _Pragma("unroll") for (int _i = 0; _i < 2; ++_i) \
;         __builtin_amdgcn_global_load_lds((const unsigned*)((const char*)(gbase) + (voff)[_i]), (LAS unsigned*)(lds + (bufoff) + ldsw + _i * 8192), 16, 0, 0); } while (0)
; #define PG8_LDA(dst, b, h) do { _Pragma("unroll") for (int m = 0; m < 4; ++m) _Pragma("unroll") for (int k = 0; k < 2; ++k) dst[m][k] = *(const LAS bf16x8*)(lds + PG8_SA(b, h) + aoff + m * 2048 + k * 1024); } while (0)
; #define PG8_MMA(ai, bj, At, Bt) do { __builtin_amdgcn_s_setprio(1); _Pragma("unroll") for (int m = 0; m < 4; ++m) _Pragma("unroll") for (int n = 0; n < 2; ++n) _Pragma("unroll") for (int k = 0; k < 2; ++k) \
;         acc[ai][bj][m][n] = __builtin_amdgcn_mfma_f32_16x16x32_bf16(Bt[n][k], At[m][k], acc[ai][bj][m][n], 0, 0, 0); __builtin_amdgcn_s_setprio(0); } while (0)
; #define PG8_WAIT_V(n) asm volatile("s_waitcnt vmcnt(" #n ")" ::: "memory")
; #define PG8_WAIT_L(n) asm volatile("s_waitcnt lgkmcnt(" #n ")" ::: "memory")
; #define PG8_BAR __builtin_amdgcn_s_barrier()
; #define PG8_SCHED __builtin_amdgcn_sched_barrier(0)
; template <class Epi, bool ALIGN_EPI, bool SP2, bool ROWHALF = false>
; DI void gemm_phase(LAS unsigned char* lds, const Gemm g, const StaticOrder& S, const Epi& E) {
;     ...
;             if constexpr (!ROWHALF) { PG8_LDA(At, 1, 1); } PG8_STAGE(PG8_SB(1, 0), b3, voffB); PG8_STAGE(PG8_SB(1, 1), b3 + hstepB, voffB); PG8_STAGE(PG8_SA(1, 0), a3 + hA0, voffA);
;             PG8_WAIT_V(8); PG8_WAIT_L(0); PG8_BAR; if constexpr (!ROWHALF) { PG8_MMA(1, 0, At, B0); PG8_MMA(1, 1, At, B1); } PG8_BAR; PG8_SCHED;
	s_add_i32 s36, s82, s4
	v_lshl_add_u64 v[144:145], v[144:145], 0, s[38:39]
	s_mov_b32 m0, s36
	ds_read_b128 v[180:183], v149 offset:49152
	ds_read_b128 v[184:187], v149 offset:50176
	ds_read_b128 v[216:219], v149 offset:51200
	ds_read_b128 v[220:223], v149 offset:52224
	ds_read_b128 v[224:227], v149 offset:53248
	ds_read_b128 v[228:231], v149 offset:54272
	ds_read_b128 v[232:235], v149 offset:55296
	ds_read_b128 v[236:239], v149 offset:56320
	global_load_lds_dwordx4 v[144:145], off
	v_lshl_add_u64 v[144:145], v[192:193], 0, s[38:39]
	s_add_i32 m0, s36, 0x2000
	s_add_i32 s36, s83, s4
	global_load_lds_dwordx4 v[144:145], off
	v_lshl_add_u64 v[144:145], v[194:195], 0, s[38:39]
	s_mov_b32 m0, s36
	s_nop 0
	global_load_lds_dwordx4 v[144:145], off
	v_lshl_add_u64 v[144:145], v[240:241], 0, s[38:39]
	s_add_i32 m0, s36, 0x2000
	s_nop 0
	global_load_lds_dwordx4 v[144:145], off
	v_lshl_add_u64 v[144:145], v[242:243], 0, s[38:39]
	s_mov_b32 m0, s26
	s_nop 0
	global_load_lds_dwordx4 v[144:145], off
	v_lshl_add_u64 v[144:145], v[244:245], 0, s[38:39]
	s_mov_b32 m0, s27
	s_nop 0
	global_load_lds_dwordx4 v[144:145], off
	s_waitcnt vmcnt(8)
	s_waitcnt lgkmcnt(0)
	v_mfma_f32_16x16x32_bf16 v[60:63], v[130:133], v[180:183], v[60:63]
	v_mfma_f32_16x16x32_bf16 v[56:59], v[154:157], v[180:183], v[56:59]
	v_mfma_f32_16x16x32_bf16 v[44:47], v[130:133], v[216:219], v[44:47]
	v_mfma_f32_16x16x32_bf16 v[40:43], v[154:157], v[216:219], v[40:43]
	s_barrier
	v_mfma_f32_16x16x32_bf16 v[28:31], v[130:133], v[224:227], v[28:31]
	v_mfma_f32_16x16x32_bf16 v[24:27], v[154:157], v[224:227], v[24:27]
	v_mfma_f32_16x16x32_bf16 v[12:15], v[130:133], v[232:235], v[12:15]
	v_mfma_f32_16x16x32_bf16 v[8:11], v[154:157], v[232:235], v[8:11]
	v_mfma_f32_16x16x32_bf16 v[60:63], v[150:153], v[184:187], v[60:63]
	v_mfma_f32_16x16x32_bf16 v[56:59], v[158:161], v[184:187], v[56:59]
	v_mfma_f32_16x16x32_bf16 v[44:47], v[150:153], v[220:223], v[44:47]
	v_mfma_f32_16x16x32_bf16 v[40:43], v[158:161], v[220:223], v[40:43]
	v_mfma_f32_16x16x32_bf16 v[28:31], v[150:153], v[228:231], v[28:31]
	v_mfma_f32_16x16x32_bf16 v[24:27], v[158:161], v[228:231], v[24:27]
	v_mfma_f32_16x16x32_bf16 v[12:15], v[150:153], v[236:239], v[12:15]
	v_mfma_f32_16x16x32_bf16 v[8:11], v[158:161], v[236:239], v[8:11]
	v_mfma_f32_16x16x32_bf16 v[52:55], v[164:167], v[180:183], v[52:55]
	v_mfma_f32_16x16x32_bf16 v[48:51], v[172:175], v[180:183], v[48:51]
	v_mfma_f32_16x16x32_bf16 v[36:39], v[164:167], v[216:219], v[36:39]
	v_mfma_f32_16x16x32_bf16 v[32:35], v[172:175], v[216:219], v[32:35]
	v_mfma_f32_16x16x32_bf16 v[20:23], v[164:167], v[224:227], v[20:23]
	v_mfma_f32_16x16x32_bf16 v[16:19], v[172:175], v[224:227], v[16:19]
	v_mfma_f32_16x16x32_bf16 v[4:7], v[164:167], v[232:235], v[4:7]
	v_mfma_f32_16x16x32_bf16 v[0:3], v[172:175], v[232:235], v[0:3]
	v_mfma_f32_16x16x32_bf16 v[52:55], v[168:171], v[184:187], v[52:55]
	v_mfma_f32_16x16x32_bf16 v[48:51], v[176:179], v[184:187], v[48:51]
	v_mfma_f32_16x16x32_bf16 v[36:39], v[168:171], v[220:223], v[36:39]
	v_mfma_f32_16x16x32_bf16 v[32:35], v[176:179], v[220:223], v[32:35]
	v_mfma_f32_16x16x32_bf16 v[20:23], v[168:171], v[228:231], v[20:23]
	v_mfma_f32_16x16x32_bf16 v[16:19], v[176:179], v[228:231], v[16:19]
	v_mfma_f32_16x16x32_bf16 v[4:7], v[168:171], v[236:239], v[4:7]
	v_mfma_f32_16x16x32_bf16 v[0:3], v[176:179], v[236:239], v[0:3]
	s_barrier
	s_add_u32 s76, s76, 0x100
	s_addc_u32 s77, s77, 0
	s_add_u32 s20, s20, 0x100
	s_addc_u32 s21, s21, 0
	s_cmp_ge_u32 s81, s29
	s_mov_b32 s78, s81
	s_cbranch_scc0 .LBB0_122

; #define PG8_STAGE(bufoff, gbase, voff) do { _Pragma("unroll") for (int _i = 0; _i < 2; ++_i) \
;         __builtin_amdgcn_global_load_lds((const unsigned*)((const char*)(gbase) + (voff)[_i]), (LAS unsigned*)(lds + (bufoff) + ldsw + _i * 8192), 16, 0, 0); } while (0)
; #define PG8_LDA(dst, b, h) do { _Pragma("unroll") for (int m = 0; m < 4; ++m) _Pragma("unroll") for (int k = 0; k < 2; ++k) dst[m][k] = *(const LAS bf16x8*)(lds + PG8_SA(b, h) + aoff + m * 2048 + k * 1024); } while (0)
; #define PG8_LDB(dst, b, h) do { _Pragma("unroll") for (int n = 0; n < 2; ++n) _Pragma("unroll") for (int k = 0; k < 2; ++k) dst[n][k] = *(const LAS bf16x8*)(lds + PG8_SB(b, h) + boff + n * 2048 + k * 1024); } while (0)
; #define PG8_MMA(ai, bj, At, Bt) do { __builtin_amdgcn_s_setprio(1); _Pragma("unroll") for (int m = 0; m < 4; ++m) _Pragma("unroll") for (int n = 0; n < 2; ++n) _Pragma("unroll") for (int k = 0; k < 2; ++k) \
;         acc[ai][bj][m][n] = __builtin_amdgcn_mfma_f32_16x16x32_bf16(Bt[n][k], At[m][k], acc[ai][bj][m][n], 0, 0, 0); __builtin_amdgcn_s_setprio(0); } while (0)
; #define PG8_WAIT_V(n) asm volatile("s_waitcnt vmcnt(" #n ")" ::: "memory")
; #define PG8_WAIT_L(n) asm volatile("s_waitcnt lgkmcnt(" #n ")" ::: "memory")
; #define PG8_BAR __builtin_amdgcn_s_barrier()
; #define PG8_SCHED __builtin_amdgcn_sched_barrier(0)
; template <class Epi, bool ALIGN_EPI, bool SP2, bool ROWHALF = false>
; DI void gemm_phase(LAS unsigned char* lds, const Gemm g, const StaticOrder& S, const Epi& E) {
;     ...
;         for (int t = 0; t < nt; t += 2) {
;             const bool last = (t == nt - 2);
;             const char* a1 = cA + (size_t)(t + 1) * kstep;
;             const char* a2 = last ? nA : cA + (size_t)(t + 2) * kstep; const char* b2 = last ? nB : cB + (size_t)(t + 2) * kstep;
;             const char* a3 = a2 + kstep; const char* b3 = b2 + kstep;
;             if constexpr (SP2) {
;             PG8_LDB(B0, 0, 0); PG8_LDB(B1, 0, 1); PG8_SCHED; PG8_LDA(At, 0, 0); PG8_STAGE(PG8_SA(1, 1), a1 + hA1, voffA);
;             PG8_WAIT_V(8); PG8_WAIT_L(0); PG8_BAR; PG8_MMA(0, 0, At, B0); PG8_MMA(0, 1, At, B1); PG8_BAR; PG8_SCHED;
;             if constexpr (!ROWHALF) { PG8_LDA(At, 0, 1); } PG8_STAGE(PG8_SB(0, 0), b2, voffB); PG8_STAGE(PG8_SB(0, 1), b2 + hstepB, voffB); PG8_STAGE(PG8_SA(0, 0), a2 + hA0, voffA);
.LBB0_159:
	s_add_i32 s36, s37, 2
	s_add_u32 s78, s76, 0x80
	s_addc_u32 s79, s77, 0
	s_add_i32 s81, 0, 0x10000
	s_cmp_eq_u32 s13, s37
	s_cselect_b32 s79, s1, s79
	s_cselect_b32 s78, s0, s78
	v_add_u32_e32 v96, s81, v146
	s_cselect_b32 s83, s75, s21
	s_cselect_b32 s82, s74, s20
	s_add_i32 s37, 0, 0x14000
	ds_read_b128 v[148:151], v96
	ds_read_b128 v[152:155], v96 offset:1024
	ds_read_b128 v[156:159], v96 offset:2048
	ds_read_b128 v[164:167], v96 offset:3072
	v_add_u32_e32 v96, s37, v146
	ds_read_b128 v[168:171], v96
	ds_read_b128 v[172:175], v96 offset:1024
	ds_read_b128 v[176:179], v96 offset:2048
	ds_read_b128 v[180:183], v96 offset:3072
	v_lshl_add_u64 v[98:99], s[76:77], 0, v[140:141]
	s_add_i32 m0, s7, 0xc000
	ds_read_b128 v[184:187], v147
	ds_read_b128 v[218:221], v147 offset:1024
	ds_read_b128 v[222:225], v147 offset:2048
	ds_read_b128 v[226:229], v147 offset:3072
	ds_read_b128 v[230:233], v147 offset:4096
	ds_read_b128 v[234:237], v147 offset:5120
	ds_read_b128 v[238:241], v147 offset:6144
	ds_read_b128 v[242:245], v147 offset:7168
	global_load_lds_dwordx4 v[98:99], off
	v_lshl_add_u64 v[98:99], s[76:77], 0, v[142:143]
	s_add_i32 m0, s7, 0xe000
	s_nop 0
	global_load_lds_dwordx4 v[98:99], off
	s_waitcnt vmcnt(8)
	s_waitcnt lgkmcnt(0)
	v_mfma_f32_16x16x32_bf16 v[4:7], v[148:151], v[184:187], v[4:7]
	v_mfma_f32_16x16x32_bf16 v[0:3], v[156:159], v[184:187], v[0:3]
	v_mfma_f32_16x16x32_bf16 v[20:23], v[148:151], v[222:225], v[20:23]
	v_mfma_f32_16x16x32_bf16 v[16:19], v[156:159], v[222:225], v[16:19]
	s_barrier
	v_mfma_f32_16x16x32_bf16 v[36:39], v[148:151], v[230:233], v[36:39]
	v_mfma_f32_16x16x32_bf16 v[32:35], v[156:159], v[230:233], v[32:35]
	v_mfma_f32_16x16x32_bf16 v[52:55], v[148:151], v[238:241], v[52:55]
	v_mfma_f32_16x16x32_bf16 v[48:51], v[156:159], v[238:241], v[48:51]
	v_mfma_f32_16x16x32_bf16 v[4:7], v[152:155], v[218:221], v[4:7]
	v_mfma_f32_16x16x32_bf16 v[0:3], v[164:167], v[218:221], v[0:3]
	v_mfma_f32_16x16x32_bf16 v[20:23], v[152:155], v[226:229], v[20:23]
	v_mfma_f32_16x16x32_bf16 v[16:19], v[164:167], v[226:229], v[16:19]
	v_mfma_f32_16x16x32_bf16 v[36:39], v[152:155], v[234:237], v[36:39]
	v_mfma_f32_16x16x32_bf16 v[32:35], v[164:167], v[234:237], v[32:35]
	v_mfma_f32_16x16x32_bf16 v[52:55], v[152:155], v[242:245], v[52:55]
	v_mfma_f32_16x16x32_bf16 v[48:51], v[164:167], v[242:245], v[48:51]
	v_mfma_f32_16x16x32_bf16 v[12:15], v[168:171], v[184:187], v[12:15]
	v_mfma_f32_16x16x32_bf16 v[8:11], v[176:179], v[184:187], v[8:11]
	v_mfma_f32_16x16x32_bf16 v[28:31], v[168:171], v[222:225], v[28:31]
	v_mfma_f32_16x16x32_bf16 v[24:27], v[176:179], v[222:225], v[24:27]
	v_mfma_f32_16x16x32_bf16 v[44:47], v[168:171], v[230:233], v[44:47]
	v_mfma_f32_16x16x32_bf16 v[40:43], v[176:179], v[230:233], v[40:43]
	v_mfma_f32_16x16x32_bf16 v[60:63], v[168:171], v[238:241], v[60:63]
	v_mfma_f32_16x16x32_bf16 v[56:59], v[176:179], v[238:241], v[56:59]
	v_mfma_f32_16x16x32_bf16 v[12:15], v[172:175], v[218:221], v[12:15]
	v_mfma_f32_16x16x32_bf16 v[8:11], v[180:183], v[218:221], v[8:11]
	v_mfma_f32_16x16x32_bf16 v[28:31], v[172:175], v[226:229], v[28:31]
	v_mfma_f32_16x16x32_bf16 v[24:27], v[180:183], v[226:229], v[24:27]
	v_mfma_f32_16x16x32_bf16 v[44:47], v[172:175], v[234:237], v[44:47]
	v_mfma_f32_16x16x32_bf16 v[40:43], v[180:183], v[234:237], v[40:43]
	v_mfma_f32_16x16x32_bf16 v[60:63], v[172:175], v[242:245], v[60:63]
	v_mfma_f32_16x16x32_bf16 v[56:59], v[180:183], v[242:245], v[56:59]
	s_barrier
	s_add_i32 s81, s81, s4
	v_lshl_add_u64 v[160:161], s[82:83], 0, v[136:137]
	s_mov_b32 m0, s81
	ds_read_b128 v[184:187], v147 offset:16384
	ds_read_b128 v[218:221], v147 offset:17408
	ds_read_b128 v[222:225], v147 offset:18432
	ds_read_b128 v[226:229], v147 offset:19456
	ds_read_b128 v[230:233], v147 offset:20480
	ds_read_b128 v[234:237], v147 offset:21504
	ds_read_b128 v[238:241], v147 offset:22528
	ds_read_b128 v[242:245], v147 offset:23552
	global_load_lds_dwordx4 v[160:161], off
	s_add_i32 m0, s81, 0x2000
	v_lshl_add_u64 v[246:247], s[82:83], 0, v[108:109]
	s_add_u32 s82, s82, s28
	s_addc_u32 s83, s83, 0
	s_add_i32 s37, s37, s4
	global_load_lds_dwordx4 v[246:247], off
	v_lshl_add_u64 v[248:249], s[82:83], 0, v[136:137]
	s_mov_b32 m0, s37
	v_lshl_add_u64 v[250:251], s[82:83], 0, v[108:109]
	global_load_lds_dwordx4 v[248:249], off
	s_add_i32 m0, s37, 0x2000
	v_lshl_add_u64 v[192:193], s[78:79], 0, v[138:139]
	global_load_lds_dwordx4 v[250:251], off
	s_mov_b32 m0, s7
	v_lshl_add_u64 v[194:195], s[78:79], 0, v[134:135]
	global_load_lds_dwordx4 v[192:193], off
	s_mov_b32 m0, s8
	s_nop 0
	global_load_lds_dwordx4 v[194:195], off
	s_waitcnt vmcnt(8)
	s_waitcnt lgkmcnt(0)
	v_mfma_f32_16x16x32_bf16 v[68:71], v[148:151], v[184:187], v[68:71]
	v_mfma_f32_16x16x32_bf16 v[64:67], v[156:159], v[184:187], v[64:67]
	v_mfma_f32_16x16x32_bf16 v[84:87], v[148:151], v[222:225], v[84:87]
	v_mfma_f32_16x16x32_bf16 v[80:83], v[156:159], v[222:225], v[80:83]
	s_barrier
; #define PG8_STAGE(bufoff, gbase, voff) do { _Pragma("unroll") for (int _i = 0; _i < 2; ++_i) \
;         __builtin_amdgcn_global_load_lds((const unsigned*)((const char*)(gbase) + (voff)[_i]), (LAS unsigned*)(lds + (bufoff) + ldsw + _i * 8192), 16, 0, 0); } while (0)
; #define PG8_LDA(dst, b, h) do { _Pragma("unroll") for (int m = 0; m < 4; ++m) _Pragma("unroll") for (int k = 0; k < 2; ++k) dst[m][k] = *(const LAS bf16x8*)(lds + PG8_SA(b, h) + aoff + m * 2048 + k * 1024); } while (0)
; #define PG8_LDB(dst, b, h) do { _Pragma("unroll") for (int n = 0; n < 2; ++n) _Pragma("unroll") for (int k = 0; k < 2; ++k) dst[n][k] = *(const LAS bf16x8*)(lds + PG8_SB(b, h) + boff + n * 2048 + k * 1024); } while (0)
; #define PG8_MMA(ai, bj, At, Bt) do { __builtin_amdgcn_s_setprio(1); _Pragma("unroll") for (int m = 0; m < 4; ++m) _Pragma("unroll") for (int n = 0; n < 2; ++n) _Pragma("unroll") for (int k = 0; k < 2; ++k) \
;         acc[ai][bj][m][n] = __builtin_amdgcn_mfma_f32_16x16x32_bf16(Bt[n][k], At[m][k], acc[ai][bj][m][n], 0, 0, 0); __builtin_amdgcn_s_setprio(0); } while (0)
; #define PG8_WAIT_V(n) asm volatile("s_waitcnt vmcnt(" #n ")" ::: "memory")
; #define PG8_WAIT_L(n) asm volatile("s_waitcnt lgkmcnt(" #n ")" ::: "memory")
; #define PG8_BAR __builtin_amdgcn_s_barrier()
; #define PG8_SCHED __builtin_amdgcn_sched_barrier(0)
; template <class Epi, bool ALIGN_EPI, bool SP2, bool ROWHALF = false>
; DI void gemm_phase(LAS unsigned char* lds, const Gemm g, const StaticOrder& S, const Epi& E) {
;     ...
;             PG8_WAIT_V(8); PG8_WAIT_L(0); PG8_BAR; if constexpr (!ROWHALF) { PG8_MMA(1, 0, At, B0); PG8_MMA(1, 1, At, B1); } PG8_BAR; PG8_SCHED;
;             PG8_LDB(B0, 1, 0); PG8_LDB(B1, 1, 1); PG8_SCHED; PG8_LDA(At, 1, 0); PG8_STAGE(PG8_SA(0, 1), a2 + hA1, voffA);
;             PG8_WAIT_V(8); PG8_WAIT_L(0); PG8_BAR; PG8_MMA(0, 0, At, B0); PG8_MMA(0, 1, At, B1); PG8_BAR; PG8_SCHED;
	v_mfma_f32_16x16x32_bf16 v[114:117], v[148:151], v[230:233], v[114:117]
	v_mfma_f32_16x16x32_bf16 v[104:107], v[156:159], v[230:233], v[104:107]
	v_mfma_f32_16x16x32_bf16 v[118:121], v[148:151], v[238:241], v[118:121]
	v_mfma_f32_16x16x32_bf16 v[110:113], v[156:159], v[238:241], v[110:113]
	v_mfma_f32_16x16x32_bf16 v[68:71], v[152:155], v[218:221], v[68:71]
	v_mfma_f32_16x16x32_bf16 v[64:67], v[164:167], v[218:221], v[64:67]
	v_mfma_f32_16x16x32_bf16 v[84:87], v[152:155], v[226:229], v[84:87]
	v_mfma_f32_16x16x32_bf16 v[80:83], v[164:167], v[226:229], v[80:83]
	v_mfma_f32_16x16x32_bf16 v[114:117], v[152:155], v[234:237], v[114:117]
	v_mfma_f32_16x16x32_bf16 v[104:107], v[164:167], v[234:237], v[104:107]
	v_mfma_f32_16x16x32_bf16 v[118:121], v[152:155], v[242:245], v[118:121]
	v_mfma_f32_16x16x32_bf16 v[110:113], v[164:167], v[242:245], v[110:113]
	v_mfma_f32_16x16x32_bf16 v[76:79], v[168:171], v[184:187], v[76:79]
	v_mfma_f32_16x16x32_bf16 v[72:75], v[176:179], v[184:187], v[72:75]
	v_mfma_f32_16x16x32_bf16 v[92:95], v[168:171], v[222:225], v[92:95]
	v_mfma_f32_16x16x32_bf16 v[88:91], v[176:179], v[222:225], v[88:91]
	v_mfma_f32_16x16x32_bf16 v[126:129], v[168:171], v[230:233], v[126:129]
	v_mfma_f32_16x16x32_bf16 v[122:125], v[176:179], v[230:233], v[122:125]
	v_mfma_f32_16x16x32_bf16 v[98:101], v[168:171], v[238:241], v[100:103]
	v_mfma_f32_16x16x32_bf16 v[130:133], v[176:179], v[238:241], v[130:133]
	v_mfma_f32_16x16x32_bf16 v[76:79], v[172:175], v[218:221], v[76:79]
	v_mfma_f32_16x16x32_bf16 v[72:75], v[180:183], v[218:221], v[72:75]
	v_mfma_f32_16x16x32_bf16 v[92:95], v[172:175], v[226:229], v[92:95]
	v_mfma_f32_16x16x32_bf16 v[88:91], v[180:183], v[226:229], v[88:91]
	v_mfma_f32_16x16x32_bf16 v[126:129], v[172:175], v[234:237], v[126:129]
	v_mfma_f32_16x16x32_bf16 v[122:125], v[180:183], v[234:237], v[122:125]
	v_mfma_f32_16x16x32_bf16 v[98:101], v[172:175], v[242:245], v[98:101]
	v_mfma_f32_16x16x32_bf16 v[130:133], v[180:183], v[242:245], v[130:133]
	s_barrier
	s_add_i32 s37, 0, 0x18000
	v_add_u32_e32 v96, s37, v146
	s_add_i32 s81, 0, 0x1c000
	ds_read_b128 v[148:151], v96
	ds_read_b128 v[152:155], v96 offset:1024
	ds_read_b128 v[156:159], v96 offset:2048
	ds_read_b128 v[164:167], v96 offset:3072
	v_add_u32_e32 v96, s81, v146
	ds_read_b128 v[168:171], v96
	ds_read_b128 v[172:175], v96 offset:1024
	ds_read_b128 v[176:179], v96 offset:2048
	ds_read_b128 v[180:183], v96 offset:3072
	s_add_u32 s78, s78, s18
	s_addc_u32 s79, s79, 0
	s_mov_b32 m0, s9
	v_lshl_add_u64 v[102:103], s[78:79], 0, v[138:139]
	ds_read_b128 v[184:187], v147 offset:32768
	ds_read_b128 v[218:221], v147 offset:33792
	ds_read_b128 v[222:225], v147 offset:34816
	ds_read_b128 v[226:229], v147 offset:35840
	ds_read_b128 v[230:233], v147 offset:36864
	ds_read_b128 v[234:237], v147 offset:37888
	ds_read_b128 v[238:241], v147 offset:38912
	ds_read_b128 v[242:245], v147 offset:39936
	global_load_lds_dwordx4 v[102:103], off
	v_lshl_add_u64 v[102:103], s[78:79], 0, v[134:135]
	s_mov_b32 m0, s10
	s_nop 0
	global_load_lds_dwordx4 v[102:103], off
	s_waitcnt vmcnt(8)
	s_waitcnt lgkmcnt(0)
	v_mfma_f32_16x16x32_bf16 v[4:7], v[148:151], v[184:187], v[4:7]
	v_mfma_f32_16x16x32_bf16 v[0:3], v[156:159], v[184:187], v[0:3]
	v_mfma_f32_16x16x32_bf16 v[20:23], v[148:151], v[222:225], v[20:23]
	v_mfma_f32_16x16x32_bf16 v[16:19], v[156:159], v[222:225], v[16:19]
	s_barrier
	v_mfma_f32_16x16x32_bf16 v[36:39], v[148:151], v[230:233], v[36:39]
	v_mfma_f32_16x16x32_bf16 v[32:35], v[156:159], v[230:233], v[32:35]
	v_mfma_f32_16x16x32_bf16 v[52:55], v[148:151], v[238:241], v[52:55]
	v_mfma_f32_16x16x32_bf16 v[48:51], v[156:159], v[238:241], v[48:51]
	v_mfma_f32_16x16x32_bf16 v[4:7], v[152:155], v[218:221], v[4:7]
	v_mfma_f32_16x16x32_bf16 v[0:3], v[164:167], v[218:221], v[0:3]
	v_mfma_f32_16x16x32_bf16 v[20:23], v[152:155], v[226:229], v[20:23]
	v_mfma_f32_16x16x32_bf16 v[16:19], v[164:167], v[226:229], v[16:19]
	v_mfma_f32_16x16x32_bf16 v[36:39], v[152:155], v[234:237], v[36:39]
	v_mfma_f32_16x16x32_bf16 v[32:35], v[164:167], v[234:237], v[32:35]
	v_mfma_f32_16x16x32_bf16 v[52:55], v[152:155], v[242:245], v[52:55]
	v_mfma_f32_16x16x32_bf16 v[48:51], v[164:167], v[242:245], v[48:51]
	v_mfma_f32_16x16x32_bf16 v[12:15], v[168:171], v[184:187], v[12:15]
	v_mfma_f32_16x16x32_bf16 v[8:11], v[176:179], v[184:187], v[8:11]
	v_mfma_f32_16x16x32_bf16 v[28:31], v[168:171], v[222:225], v[28:31]
	v_mfma_f32_16x16x32_bf16 v[24:27], v[176:179], v[222:225], v[24:27]
	v_mfma_f32_16x16x32_bf16 v[44:47], v[168:171], v[230:233], v[44:47]
	v_mfma_f32_16x16x32_bf16 v[40:43], v[176:179], v[230:233], v[40:43]
	v_mfma_f32_16x16x32_bf16 v[60:63], v[168:171], v[238:241], v[60:63]
	v_mfma_f32_16x16x32_bf16 v[56:59], v[176:179], v[238:241], v[56:59]
	v_mfma_f32_16x16x32_bf16 v[12:15], v[172:175], v[218:221], v[12:15]
	v_mfma_f32_16x16x32_bf16 v[8:11], v[180:183], v[218:221], v[8:11]
	v_mfma_f32_16x16x32_bf16 v[28:31], v[172:175], v[226:229], v[28:31]
	v_mfma_f32_16x16x32_bf16 v[24:27], v[180:183], v[226:229], v[24:27]
	v_mfma_f32_16x16x32_bf16 v[44:47], v[172:175], v[234:237], v[44:47]
	v_mfma_f32_16x16x32_bf16 v[40:43], v[180:183], v[234:237], v[40:43]
	v_mfma_f32_16x16x32_bf16 v[60:63], v[172:175], v[242:245], v[60:63]
	v_mfma_f32_16x16x32_bf16 v[56:59], v[180:183], v[242:245], v[56:59]
	s_barrier
; #define PG8_STAGE(bufoff, gbase, voff) do { _Pragma("unroll") for (int _i = 0; _i < 2; ++_i) \
;         __builtin_amdgcn_global_load_lds((const unsigned*)((const char*)(gbase) + (voff)[_i]), (LAS unsigned*)(lds + (bufoff) + ldsw + _i * 8192), 16, 0, 0); } while (0)
; #define PG8_LDA(dst, b, h) do { _Pragma("unroll") for (int m = 0; m < 4; ++m) _Pragma("unroll") for (int k = 0; k < 2; ++k) dst[m][k] = *(const LAS bf16x8*)(lds + PG8_SA(b, h) + aoff + m * 2048 + k * 1024); } while (0)
; #define PG8_MMA(ai, bj, At, Bt) do { __builtin_amdgcn_s_setprio(1); _Pragma("unroll") for (int m = 0; m < 4; ++m) _Pragma("unroll") for (int n = 0; n < 2; ++n) _Pragma("unroll") for (int k = 0; k < 2; ++k) \
;         acc[ai][bj][m][n] = __builtin_amdgcn_mfma_f32_16x16x32_bf16(Bt[n][k], At[m][k], acc[ai][bj][m][n], 0, 0, 0); __builtin_amdgcn_s_setprio(0); } while (0)
; #define PG8_WAIT_V(n) asm volatile("s_waitcnt vmcnt(" #n ")" ::: "memory")
; #define PG8_WAIT_L(n) asm volatile("s_waitcnt lgkmcnt(" #n ")" ::: "memory")
; #define PG8_BAR __builtin_amdgcn_s_barrier()
; #define PG8_SCHED __builtin_amdgcn_sched_barrier(0)
; template <class Epi, bool ALIGN_EPI, bool SP2, bool ROWHALF = false>
; DI void gemm_phase(LAS unsigned char* lds, const Gemm g, const StaticOrder& S, const Epi& E) {
;     ...
;             if constexpr (!ROWHALF) { PG8_LDA(At, 1, 1); } PG8_STAGE(PG8_SB(1, 0), b3, voffB); PG8_STAGE(PG8_SB(1, 1), b3 + hstepB, voffB); PG8_STAGE(PG8_SA(1, 0), a3 + hA0, voffA);
;             PG8_WAIT_V(8); PG8_WAIT_L(0); PG8_BAR; if constexpr (!ROWHALF) { PG8_MMA(1, 0, At, B0); PG8_MMA(1, 1, At, B1); } PG8_BAR; PG8_SCHED;
;     ...
;         }
;         if constexpr (ALIGN_EPI) { if (wr == 0) PG8_BAR; }
;         if constexpr (!Epi::AFTER_DRAIN) E(acc, cur, wr, wc, fr, fq);
;         if (!has_next) break;
	s_add_i32 s37, s37, s4
	v_lshl_add_u64 v[102:103], v[160:161], 0, s[38:39]
	s_mov_b32 m0, s37
	ds_read_b128 v[184:187], v147 offset:49152
	ds_read_b128 v[218:221], v147 offset:50176
	ds_read_b128 v[222:225], v147 offset:51200
	ds_read_b128 v[226:229], v147 offset:52224
	ds_read_b128 v[230:233], v147 offset:53248
	ds_read_b128 v[234:237], v147 offset:54272
	ds_read_b128 v[238:241], v147 offset:55296
	ds_read_b128 v[242:245], v147 offset:56320
	global_load_lds_dwordx4 v[102:103], off
	v_lshl_add_u64 v[102:103], v[246:247], 0, s[38:39]
	s_add_i32 m0, s37, 0x2000
	s_add_i32 s37, s81, s4
	global_load_lds_dwordx4 v[102:103], off
	v_lshl_add_u64 v[102:103], v[248:249], 0, s[38:39]
	s_mov_b32 m0, s37
	s_nop 0
	global_load_lds_dwordx4 v[102:103], off
	v_lshl_add_u64 v[102:103], v[250:251], 0, s[38:39]
	s_add_i32 m0, s37, 0x2000
	s_nop 0
	global_load_lds_dwordx4 v[102:103], off
	v_lshl_add_u64 v[102:103], v[192:193], 0, s[38:39]
	s_mov_b32 m0, s46
	s_nop 0
	global_load_lds_dwordx4 v[102:103], off
	v_lshl_add_u64 v[102:103], v[194:195], 0, s[38:39]
	s_mov_b32 m0, s47
	s_nop 0
	global_load_lds_dwordx4 v[102:103], off
	s_waitcnt vmcnt(8)
	s_waitcnt lgkmcnt(0)
	v_mfma_f32_16x16x32_bf16 v[68:71], v[148:151], v[184:187], v[68:71]
	v_mfma_f32_16x16x32_bf16 v[64:67], v[156:159], v[184:187], v[64:67]
	v_mfma_f32_16x16x32_bf16 v[84:87], v[148:151], v[222:225], v[84:87]
	v_mfma_f32_16x16x32_bf16 v[80:83], v[156:159], v[222:225], v[80:83]
	s_barrier
	v_mfma_f32_16x16x32_bf16 v[114:117], v[148:151], v[230:233], v[114:117]
	v_mfma_f32_16x16x32_bf16 v[102:105], v[156:159], v[230:233], v[104:107]
	v_mfma_f32_16x16x32_bf16 v[118:121], v[148:151], v[238:241], v[118:121]
	v_mfma_f32_16x16x32_bf16 v[110:113], v[156:159], v[238:241], v[110:113]
	v_mfma_f32_16x16x32_bf16 v[68:71], v[152:155], v[218:221], v[68:71]
	v_mfma_f32_16x16x32_bf16 v[64:67], v[164:167], v[218:221], v[64:67]
	v_mfma_f32_16x16x32_bf16 v[84:87], v[152:155], v[226:229], v[84:87]
	v_mfma_f32_16x16x32_bf16 v[80:83], v[164:167], v[226:229], v[80:83]
	v_mfma_f32_16x16x32_bf16 v[114:117], v[152:155], v[234:237], v[114:117]
	v_mfma_f32_16x16x32_bf16 v[104:107], v[164:167], v[234:237], v[102:105]
	v_mfma_f32_16x16x32_bf16 v[118:121], v[152:155], v[242:245], v[118:121]
	v_mfma_f32_16x16x32_bf16 v[110:113], v[164:167], v[242:245], v[110:113]
	v_mfma_f32_16x16x32_bf16 v[76:79], v[168:171], v[184:187], v[76:79]
	v_mfma_f32_16x16x32_bf16 v[72:75], v[176:179], v[184:187], v[72:75]
	v_mfma_f32_16x16x32_bf16 v[92:95], v[168:171], v[222:225], v[92:95]
	v_mfma_f32_16x16x32_bf16 v[88:91], v[176:179], v[222:225], v[88:91]
	v_mfma_f32_16x16x32_bf16 v[126:129], v[168:171], v[230:233], v[126:129]
	v_mfma_f32_16x16x32_bf16 v[122:125], v[176:179], v[230:233], v[122:125]
	v_mfma_f32_16x16x32_bf16 v[98:101], v[168:171], v[238:241], v[98:101]
	v_mfma_f32_16x16x32_bf16 v[130:133], v[176:179], v[238:241], v[130:133]
	v_mfma_f32_16x16x32_bf16 v[76:79], v[172:175], v[218:221], v[76:79]
	v_mfma_f32_16x16x32_bf16 v[72:75], v[180:183], v[218:221], v[72:75]
	v_mfma_f32_16x16x32_bf16 v[92:95], v[172:175], v[226:229], v[92:95]
	v_mfma_f32_16x16x32_bf16 v[88:91], v[180:183], v[226:229], v[88:91]
	v_mfma_f32_16x16x32_bf16 v[126:129], v[172:175], v[234:237], v[126:129]
	v_mfma_f32_16x16x32_bf16 v[122:125], v[180:183], v[234:237], v[122:125]
	v_mfma_f32_16x16x32_bf16 v[100:103], v[172:175], v[242:245], v[98:101]
	v_mfma_f32_16x16x32_bf16 v[130:133], v[180:183], v[242:245], v[130:133]
	s_barrier
	s_add_u32 s76, s76, 0x100
	s_addc_u32 s77, s77, 0
	s_add_u32 s20, s20, 0x100
	s_addc_u32 s21, s21, 0
	s_cmp_ge_u32 s36, s29
	s_mov_b32 s37, s36
	s_cbranch_scc0 .LBB0_159
	v_mov_b32_e32 v248, v217
	v_mov_b32_e32 v250, v207
	v_mov_b32_e32 v207, v196
	v_mov_b32_e32 v196, v197
	v_mov_b32_e32 v197, v198
	v_mov_b32_e32 v198, v199
	v_mov_b32_e32 v199, v200
	v_mov_b32_e32 v200, v201
	v_mov_b32_e32 v201, v202
	v_mov_b32_e32 v202, v203
	v_mov_b32_e32 v203, v204
	v_mov_b32_e32 v204, v205
	v_mov_b32_e32 v205, v206
	s_and_b64 vcc, exec, s[42:43]
	s_cbranch_vccnz .LBB0_152
	s_branch .LBB0_164

; #define PG8_STAGE(bufoff, gbase, voff) do { _Pragma("unroll") for (int _i = 0; _i < 2; ++_i) \
;         __builtin_amdgcn_global_load_lds((const unsigned*)((const char*)(gbase) + (voff)[_i]), (LAS unsigned*)(lds + (bufoff) + ldsw + _i * 8192), 16, 0, 0); } while (0)
; #define PG8_LDA(dst, b, h) do { _Pragma("unroll") for (int m = 0; m < 4; ++m) _Pragma("unroll") for (int k = 0; k < 2; ++k) dst[m][k] = *(const LAS bf16x8*)(lds + PG8_SA(b, h) + aoff + m * 2048 + k * 1024); } while (0)
; #define PG8_LDB(dst, b, h) do { _Pragma("unroll") for (int n = 0; n < 2; ++n) _Pragma("unroll") for (int k = 0; k < 2; ++k) dst[n][k] = *(const LAS bf16x8*)(lds + PG8_SB(b, h) + boff + n * 2048 + k * 1024); } while (0)
; #define PG8_MMA(ai, bj, At, Bt) do { __builtin_amdgcn_s_setprio(1); _Pragma("unroll") for (int m = 0; m < 4; ++m) _Pragma("unroll") for (int n = 0; n < 2; ++n) _Pragma("unroll") for (int k = 0; k < 2; ++k) \
;         acc[ai][bj][m][n] = __builtin_amdgcn_mfma_f32_16x16x32_bf16(Bt[n][k], At[m][k], acc[ai][bj][m][n], 0, 0, 0); __builtin_amdgcn_s_setprio(0); } while (0)
; #define PG8_WAIT_V(n) asm volatile("s_waitcnt vmcnt(" #n ")" ::: "memory")
; #define PG8_WAIT_L(n) asm volatile("s_waitcnt lgkmcnt(" #n ")" ::: "memory")
; #define PG8_BAR __builtin_amdgcn_s_barrier()
; #define PG8_SCHED __builtin_amdgcn_sched_barrier(0)
; template <class Epi, bool ALIGN_EPI, bool SP2, bool ROWHALF = false>
; DI void gemm_phase(LAS unsigned char* lds, const Gemm g, const StaticOrder& S, const Epi& E) {
;     ...
;         for (int t = 0; t < nt; t += 2) {
;             const bool last = (t == nt - 2);
;             const char* a1 = cA + (size_t)(t + 1) * kstep;
;             const char* a2 = last ? nA : cA + (size_t)(t + 2) * kstep; const char* b2 = last ? nB : cB + (size_t)(t + 2) * kstep;
;             const char* a3 = a2 + kstep; const char* b3 = b2 + kstep;
;             if constexpr (SP2) {
;             PG8_LDB(B0, 0, 0); PG8_LDB(B1, 0, 1); PG8_SCHED; PG8_LDA(At, 0, 0); PG8_STAGE(PG8_SA(1, 1), a1 + hA1, voffA);
;             PG8_WAIT_V(8); PG8_WAIT_L(0); PG8_BAR; PG8_MMA(0, 0, At, B0); PG8_MMA(0, 1, At, B1); PG8_BAR; PG8_SCHED;
;             if constexpr (!ROWHALF) { PG8_LDA(At, 0, 1); } PG8_STAGE(PG8_SB(0, 0), b2, voffB); PG8_STAGE(PG8_SB(0, 1), b2 + hstepB, voffB); PG8_STAGE(PG8_SA(0, 0), a2 + hA0, voffA);
.LBB0_240:
	s_add_u32 s36, s74, 0xfff80080
	s_addc_u32 s37, s75, -1
	s_add_i32 s54, 0, 0x10000
	s_cmp_eq_u32 s53, 28
	s_cselect_b32 s79, s20, s37
	s_cselect_b32 s78, s21, s36
	s_cselect_b32 s77, s29, s51
	s_cselect_b32 s76, s43, s47
	s_add_i32 s55, 0, 0x14000
	v_add_u32_e32 v156, s54, v145
	v_add_u32_e32 v160, s55, v145
	ds_read_b128 v[140:143], v156
	ds_read_b128 v[148:151], v156 offset:1024
	ds_read_b128 v[152:155], v156 offset:2048
	ds_read_b128 v[156:159], v156 offset:3072
	ds_read_b128 v[164:167], v160
	ds_read_b128 v[168:171], v160 offset:1024
	ds_read_b128 v[172:175], v160 offset:2048
	ds_read_b128 v[176:179], v160 offset:3072
	v_lshl_add_u64 v[160:161], s[74:75], 0, v[136:137]
	s_add_i32 m0, s9, 0xc000
	ds_read_b128 v[180:183], v147
	ds_read_b128 v[184:187], v147 offset:1024
	ds_read_b128 v[216:219], v147 offset:2048
	ds_read_b128 v[220:223], v147 offset:3072
	ds_read_b128 v[224:227], v147 offset:4096
	ds_read_b128 v[228:231], v147 offset:5120
	ds_read_b128 v[232:235], v147 offset:6144
	ds_read_b128 v[236:239], v147 offset:7168
	global_load_lds_dwordx4 v[160:161], off
	v_lshl_add_u64 v[160:161], s[74:75], 0, v[138:139]
	s_add_i32 m0, s9, 0xe000
	s_nop 0
	global_load_lds_dwordx4 v[160:161], off
	s_waitcnt vmcnt(8)
	s_waitcnt lgkmcnt(0)
	v_mfma_f32_16x16x32_bf16 v[126:129], v[140:143], v[180:183], v[126:129]
	v_mfma_f32_16x16x32_bf16 v[118:121], v[152:155], v[180:183], v[118:121]
	v_mfma_f32_16x16x32_bf16 v[110:113], v[140:143], v[216:219], v[110:113]
	v_mfma_f32_16x16x32_bf16 v[102:105], v[152:155], v[216:219], v[102:105]
	s_barrier
	v_mfma_f32_16x16x32_bf16 v[92:95], v[140:143], v[224:227], v[92:95]
	v_mfma_f32_16x16x32_bf16 v[84:87], v[152:155], v[224:227], v[84:87]
	v_mfma_f32_16x16x32_bf16 v[76:79], v[140:143], v[232:235], v[76:79]
	v_mfma_f32_16x16x32_bf16 v[68:71], v[152:155], v[232:235], v[68:71]
	v_mfma_f32_16x16x32_bf16 v[126:129], v[148:151], v[184:187], v[126:129]
	v_mfma_f32_16x16x32_bf16 v[118:121], v[156:159], v[184:187], v[118:121]
	v_mfma_f32_16x16x32_bf16 v[110:113], v[148:151], v[220:223], v[110:113]
	v_mfma_f32_16x16x32_bf16 v[102:105], v[156:159], v[220:223], v[102:105]
	v_mfma_f32_16x16x32_bf16 v[92:95], v[148:151], v[228:231], v[92:95]
	v_mfma_f32_16x16x32_bf16 v[84:87], v[156:159], v[228:231], v[84:87]
	v_mfma_f32_16x16x32_bf16 v[76:79], v[148:151], v[236:239], v[76:79]
	v_mfma_f32_16x16x32_bf16 v[68:71], v[156:159], v[236:239], v[68:71]
	v_mfma_f32_16x16x32_bf16 v[122:125], v[164:167], v[180:183], v[122:125]
	v_mfma_f32_16x16x32_bf16 v[114:117], v[172:175], v[180:183], v[114:117]
	v_mfma_f32_16x16x32_bf16 v[106:109], v[164:167], v[216:219], v[106:109]
	v_mfma_f32_16x16x32_bf16 v[98:101], v[172:175], v[216:219], v[98:101]
	v_mfma_f32_16x16x32_bf16 v[88:91], v[164:167], v[224:227], v[88:91]
	v_mfma_f32_16x16x32_bf16 v[80:83], v[172:175], v[224:227], v[80:83]
	v_mfma_f32_16x16x32_bf16 v[72:75], v[164:167], v[232:235], v[72:75]
	v_mfma_f32_16x16x32_bf16 v[64:67], v[172:175], v[232:235], v[64:67]
	v_mfma_f32_16x16x32_bf16 v[122:125], v[168:171], v[184:187], v[122:125]
	v_mfma_f32_16x16x32_bf16 v[114:117], v[176:179], v[184:187], v[114:117]
	v_mfma_f32_16x16x32_bf16 v[106:109], v[168:171], v[220:223], v[106:109]
	v_mfma_f32_16x16x32_bf16 v[98:101], v[176:179], v[220:223], v[98:101]
	v_mfma_f32_16x16x32_bf16 v[88:91], v[168:171], v[228:231], v[88:91]
	v_mfma_f32_16x16x32_bf16 v[80:83], v[176:179], v[228:231], v[80:83]
	v_mfma_f32_16x16x32_bf16 v[72:75], v[168:171], v[236:239], v[72:75]
	v_mfma_f32_16x16x32_bf16 v[64:67], v[176:179], v[236:239], v[64:67]
	s_barrier
	s_add_i32 s36, s54, s8
	v_lshl_add_u64 v[160:161], s[76:77], 0, v[96:97]
	s_mov_b32 m0, s36
	ds_read_b128 v[180:183], v147 offset:16384
	ds_read_b128 v[184:187], v147 offset:17408
	ds_read_b128 v[216:219], v147 offset:18432
	ds_read_b128 v[220:223], v147 offset:19456
	ds_read_b128 v[224:227], v147 offset:20480
	ds_read_b128 v[228:231], v147 offset:21504
	ds_read_b128 v[232:235], v147 offset:22528
	ds_read_b128 v[236:239], v147 offset:23552
	global_load_lds_dwordx4 v[160:161], off
	s_add_i32 m0, s36, 0x2000
	s_add_u32 s36, s76, 0x80000
	v_lshl_add_u64 v[240:241], s[76:77], 0, v[130:131]
	s_addc_u32 s37, s77, 0
	s_add_i32 s54, s55, s8
	global_load_lds_dwordx4 v[240:241], off
	v_lshl_add_u64 v[242:243], s[36:37], 0, v[96:97]
	s_mov_b32 m0, s54
	v_lshl_add_u64 v[244:245], s[78:79], 0, v[132:133]
	global_load_lds_dwordx4 v[242:243], off
	v_lshl_add_u64 v[242:243], s[36:37], 0, v[130:131]
	s_add_i32 m0, s54, 0x2000
	s_nop 0
	global_load_lds_dwordx4 v[242:243], off
	v_lshl_add_u64 v[242:243], s[78:79], 0, v[134:135]
	s_mov_b32 m0, s9
	s_nop 0
	global_load_lds_dwordx4 v[242:243], off
	s_mov_b32 m0, s10
	s_nop 0
	global_load_lds_dwordx4 v[244:245], off
	s_waitcnt vmcnt(8)
	s_waitcnt lgkmcnt(0)
	v_mfma_f32_16x16x32_bf16 v[60:63], v[140:143], v[180:183], v[60:63]
	v_mfma_f32_16x16x32_bf16 v[52:55], v[152:155], v[180:183], v[52:55]
	v_mfma_f32_16x16x32_bf16 v[44:47], v[140:143], v[216:219], v[44:47]
	v_mfma_f32_16x16x32_bf16 v[36:39], v[152:155], v[216:219], v[36:39]
	s_barrier
; #define PG8_STAGE(bufoff, gbase, voff) do { _Pragma("unroll") for (int _i = 0; _i < 2; ++_i) \
;         __builtin_amdgcn_global_load_lds((const unsigned*)((const char*)(gbase) + (voff)[_i]), (LAS unsigned*)(lds + (bufoff) + ldsw + _i * 8192), 16, 0, 0); } while (0)
; #define PG8_LDA(dst, b, h) do { _Pragma("unroll") for (int m = 0; m < 4; ++m) _Pragma("unroll") for (int k = 0; k < 2; ++k) dst[m][k] = *(const LAS bf16x8*)(lds + PG8_SA(b, h) + aoff + m * 2048 + k * 1024); } while (0)
; #define PG8_LDB(dst, b, h) do { _Pragma("unroll") for (int n = 0; n < 2; ++n) _Pragma("unroll") for (int k = 0; k < 2; ++k) dst[n][k] = *(const LAS bf16x8*)(lds + PG8_SB(b, h) + boff + n * 2048 + k * 1024); } while (0)
; #define PG8_MMA(ai, bj, At, Bt) do { __builtin_amdgcn_s_setprio(1); _Pragma("unroll") for (int m = 0; m < 4; ++m) _Pragma("unroll") for (int n = 0; n < 2; ++n) _Pragma("unroll") for (int k = 0; k < 2; ++k) \
;         acc[ai][bj][m][n] = __builtin_amdgcn_mfma_f32_16x16x32_bf16(Bt[n][k], At[m][k], acc[ai][bj][m][n], 0, 0, 0); __builtin_amdgcn_s_setprio(0); } while (0)
; #define PG8_WAIT_V(n) asm volatile("s_waitcnt vmcnt(" #n ")" ::: "memory")
; #define PG8_WAIT_L(n) asm volatile("s_waitcnt lgkmcnt(" #n ")" ::: "memory")
; #define PG8_BAR __builtin_amdgcn_s_barrier()
; #define PG8_SCHED __builtin_amdgcn_sched_barrier(0)
; template <class Epi, bool ALIGN_EPI, bool SP2, bool ROWHALF = false>
; DI void gemm_phase(LAS unsigned char* lds, const Gemm g, const StaticOrder& S, const Epi& E) {
;     ...
;             PG8_WAIT_V(8); PG8_WAIT_L(0); PG8_BAR; if constexpr (!ROWHALF) { PG8_MMA(1, 0, At, B0); PG8_MMA(1, 1, At, B1); } PG8_BAR; PG8_SCHED;
;             PG8_LDB(B0, 1, 0); PG8_LDB(B1, 1, 1); PG8_SCHED; PG8_LDA(At, 1, 0); PG8_STAGE(PG8_SA(0, 1), a2 + hA1, voffA);
;             PG8_WAIT_V(8); PG8_WAIT_L(0); PG8_BAR; PG8_MMA(0, 0, At, B0); PG8_MMA(0, 1, At, B1); PG8_BAR; PG8_SCHED;
	v_mfma_f32_16x16x32_bf16 v[28:31], v[140:143], v[224:227], v[28:31]
	v_mfma_f32_16x16x32_bf16 v[20:23], v[152:155], v[224:227], v[20:23]
	v_mfma_f32_16x16x32_bf16 v[12:15], v[140:143], v[232:235], v[12:15]
	v_mfma_f32_16x16x32_bf16 v[4:7], v[152:155], v[232:235], v[4:7]
	v_mfma_f32_16x16x32_bf16 v[60:63], v[148:151], v[184:187], v[60:63]
	v_mfma_f32_16x16x32_bf16 v[52:55], v[156:159], v[184:187], v[52:55]
	v_mfma_f32_16x16x32_bf16 v[44:47], v[148:151], v[220:223], v[44:47]
	v_mfma_f32_16x16x32_bf16 v[36:39], v[156:159], v[220:223], v[36:39]
	v_mfma_f32_16x16x32_bf16 v[28:31], v[148:151], v[228:231], v[28:31]
	v_mfma_f32_16x16x32_bf16 v[20:23], v[156:159], v[228:231], v[20:23]
	v_mfma_f32_16x16x32_bf16 v[12:15], v[148:151], v[236:239], v[12:15]
	v_mfma_f32_16x16x32_bf16 v[4:7], v[156:159], v[236:239], v[4:7]
	v_mfma_f32_16x16x32_bf16 v[56:59], v[164:167], v[180:183], v[56:59]
	v_mfma_f32_16x16x32_bf16 v[48:51], v[172:175], v[180:183], v[48:51]
	v_mfma_f32_16x16x32_bf16 v[40:43], v[164:167], v[216:219], v[40:43]
	v_mfma_f32_16x16x32_bf16 v[32:35], v[172:175], v[216:219], v[32:35]
	v_mfma_f32_16x16x32_bf16 v[24:27], v[164:167], v[224:227], v[24:27]
	v_mfma_f32_16x16x32_bf16 v[16:19], v[172:175], v[224:227], v[16:19]
	v_mfma_f32_16x16x32_bf16 v[8:11], v[164:167], v[232:235], v[8:11]
	v_mfma_f32_16x16x32_bf16 v[0:3], v[172:175], v[232:235], v[0:3]
	v_mfma_f32_16x16x32_bf16 v[56:59], v[168:171], v[184:187], v[56:59]
	v_mfma_f32_16x16x32_bf16 v[48:51], v[176:179], v[184:187], v[48:51]
	v_mfma_f32_16x16x32_bf16 v[40:43], v[168:171], v[220:223], v[40:43]
	v_mfma_f32_16x16x32_bf16 v[32:35], v[176:179], v[220:223], v[32:35]
	v_mfma_f32_16x16x32_bf16 v[24:27], v[168:171], v[228:231], v[24:27]
	v_mfma_f32_16x16x32_bf16 v[16:19], v[176:179], v[228:231], v[16:19]
	v_mfma_f32_16x16x32_bf16 v[8:11], v[168:171], v[236:239], v[8:11]
	v_mfma_f32_16x16x32_bf16 v[0:3], v[176:179], v[236:239], v[0:3]
	s_barrier
	s_add_i32 s54, 0, 0x18000
	s_add_i32 s55, 0, 0x1c000
	v_add_u32_e32 v156, s54, v145
	v_add_u32_e32 v176, s55, v145
	ds_read_b128 v[140:143], v156
	ds_read_b128 v[148:151], v156 offset:1024
	ds_read_b128 v[152:155], v156 offset:2048
	ds_read_b128 v[156:159], v156 offset:3072
	ds_read_b128 v[164:167], v176
	ds_read_b128 v[168:171], v176 offset:1024
	ds_read_b128 v[172:175], v176 offset:2048
	ds_read_b128 v[176:179], v176 offset:3072
	s_add_u32 s36, s78, 0x80000
	s_addc_u32 s37, s79, 0
	s_mov_b32 m0, s11
	v_lshl_add_u64 v[246:247], s[36:37], 0, v[134:135]
	ds_read_b128 v[180:183], v147 offset:32768
	ds_read_b128 v[184:187], v147 offset:33792
	ds_read_b128 v[216:219], v147 offset:34816
	ds_read_b128 v[220:223], v147 offset:35840
	ds_read_b128 v[224:227], v147 offset:36864
	ds_read_b128 v[228:231], v147 offset:37888
	ds_read_b128 v[232:235], v147 offset:38912
	ds_read_b128 v[236:239], v147 offset:39936
	global_load_lds_dwordx4 v[246:247], off
	v_lshl_add_u64 v[246:247], s[36:37], 0, v[132:133]
	s_mov_b32 m0, s12
	s_nop 0
	global_load_lds_dwordx4 v[246:247], off
	s_waitcnt vmcnt(8)
	s_waitcnt lgkmcnt(0)
	v_mfma_f32_16x16x32_bf16 v[126:129], v[140:143], v[180:183], v[126:129]
	v_mfma_f32_16x16x32_bf16 v[118:121], v[152:155], v[180:183], v[118:121]
	v_mfma_f32_16x16x32_bf16 v[110:113], v[140:143], v[216:219], v[110:113]
	v_mfma_f32_16x16x32_bf16 v[102:105], v[152:155], v[216:219], v[102:105]
	s_barrier
	v_mfma_f32_16x16x32_bf16 v[92:95], v[140:143], v[224:227], v[92:95]
	v_mfma_f32_16x16x32_bf16 v[84:87], v[152:155], v[224:227], v[84:87]
	v_mfma_f32_16x16x32_bf16 v[76:79], v[140:143], v[232:235], v[76:79]
	v_mfma_f32_16x16x32_bf16 v[68:71], v[152:155], v[232:235], v[68:71]
	v_mfma_f32_16x16x32_bf16 v[126:129], v[148:151], v[184:187], v[126:129]
	v_mfma_f32_16x16x32_bf16 v[118:121], v[156:159], v[184:187], v[118:121]
	v_mfma_f32_16x16x32_bf16 v[110:113], v[148:151], v[220:223], v[110:113]
	v_mfma_f32_16x16x32_bf16 v[102:105], v[156:159], v[220:223], v[102:105]
	v_mfma_f32_16x16x32_bf16 v[92:95], v[148:151], v[228:231], v[92:95]
	v_mfma_f32_16x16x32_bf16 v[84:87], v[156:159], v[228:231], v[84:87]
	v_mfma_f32_16x16x32_bf16 v[76:79], v[148:151], v[236:239], v[76:79]
	v_mfma_f32_16x16x32_bf16 v[68:71], v[156:159], v[236:239], v[68:71]
	v_mfma_f32_16x16x32_bf16 v[122:125], v[164:167], v[180:183], v[122:125]
	v_mfma_f32_16x16x32_bf16 v[114:117], v[172:175], v[180:183], v[114:117]
	v_mfma_f32_16x16x32_bf16 v[106:109], v[164:167], v[216:219], v[106:109]
	v_mfma_f32_16x16x32_bf16 v[98:101], v[172:175], v[216:219], v[98:101]
	v_mfma_f32_16x16x32_bf16 v[88:91], v[164:167], v[224:227], v[88:91]
	v_mfma_f32_16x16x32_bf16 v[80:83], v[172:175], v[224:227], v[80:83]
	v_mfma_f32_16x16x32_bf16 v[72:75], v[164:167], v[232:235], v[72:75]
	v_mfma_f32_16x16x32_bf16 v[64:67], v[172:175], v[232:235], v[64:67]
	v_mfma_f32_16x16x32_bf16 v[122:125], v[168:171], v[184:187], v[122:125]
	v_mfma_f32_16x16x32_bf16 v[114:117], v[176:179], v[184:187], v[114:117]
	v_mfma_f32_16x16x32_bf16 v[106:109], v[168:171], v[220:223], v[106:109]
	v_mfma_f32_16x16x32_bf16 v[98:101], v[176:179], v[220:223], v[98:101]
	v_mfma_f32_16x16x32_bf16 v[88:91], v[168:171], v[228:231], v[88:91]
	v_mfma_f32_16x16x32_bf16 v[80:83], v[176:179], v[228:231], v[80:83]
	v_mfma_f32_16x16x32_bf16 v[72:75], v[168:171], v[236:239], v[72:75]
	v_mfma_f32_16x16x32_bf16 v[64:67], v[176:179], v[236:239], v[64:67]
	s_barrier
; #define PG8_STAGE(bufoff, gbase, voff) do { _Pragma("unroll") for (int _i = 0; _i < 2; ++_i) \
;         __builtin_amdgcn_global_load_lds((const unsigned*)((const char*)(gbase) + (voff)[_i]), (LAS unsigned*)(lds + (bufoff) + ldsw + _i * 8192), 16, 0, 0); } while (0)
; #define PG8_LDA(dst, b, h) do { _Pragma("unroll") for (int m = 0; m < 4; ++m) _Pragma("unroll") for (int k = 0; k < 2; ++k) dst[m][k] = *(const LAS bf16x8*)(lds + PG8_SA(b, h) + aoff + m * 2048 + k * 1024); } while (0)
; #define PG8_MMA(ai, bj, At, Bt) do { __builtin_amdgcn_s_setprio(1); _Pragma("unroll") for (int m = 0; m < 4; ++m) _Pragma("unroll") for (int n = 0; n < 2; ++n) _Pragma("unroll") for (int k = 0; k < 2; ++k) \
;         acc[ai][bj][m][n] = __builtin_amdgcn_mfma_f32_16x16x32_bf16(Bt[n][k], At[m][k], acc[ai][bj][m][n], 0, 0, 0); __builtin_amdgcn_s_setprio(0); } while (0)
; #define PG8_WAIT_V(n) asm volatile("s_waitcnt vmcnt(" #n ")" ::: "memory")
; #define PG8_WAIT_L(n) asm volatile("s_waitcnt lgkmcnt(" #n ")" ::: "memory")
; #define PG8_BAR __builtin_amdgcn_s_barrier()
; #define PG8_SCHED __builtin_amdgcn_sched_barrier(0)
; template <class Epi, bool ALIGN_EPI, bool SP2, bool ROWHALF = false>
; DI void gemm_phase(LAS unsigned char* lds, const Gemm g, const StaticOrder& S, const Epi& E) {
;     ...
;             if constexpr (!ROWHALF) { PG8_LDA(At, 1, 1); } PG8_STAGE(PG8_SB(1, 0), b3, voffB); PG8_STAGE(PG8_SB(1, 1), b3 + hstepB, voffB); PG8_STAGE(PG8_SA(1, 0), a3 + hA0, voffA);
;             PG8_WAIT_V(8); PG8_WAIT_L(0); PG8_BAR; if constexpr (!ROWHALF) { PG8_MMA(1, 0, At, B0); PG8_MMA(1, 1, At, B1); } PG8_BAR; PG8_SCHED;
	s_add_i32 s36, s54, s8
	v_lshl_add_u64 v[160:161], v[160:161], 0, s[38:39]
	s_mov_b32 m0, s36
	ds_read_b128 v[180:183], v147 offset:49152
	ds_read_b128 v[184:187], v147 offset:50176
	ds_read_b128 v[216:219], v147 offset:51200
	ds_read_b128 v[220:223], v147 offset:52224
	ds_read_b128 v[224:227], v147 offset:53248
	ds_read_b128 v[228:231], v147 offset:54272
	ds_read_b128 v[232:235], v147 offset:55296
	ds_read_b128 v[236:239], v147 offset:56320
	global_load_lds_dwordx4 v[160:161], off
	s_add_i32 m0, s36, 0x2000
	s_add_u32 s36, s76, 0x80080
	v_lshl_add_u64 v[160:161], v[240:241], 0, s[38:39]
	s_addc_u32 s37, s77, 0
	s_add_i32 s54, s55, s8
	global_load_lds_dwordx4 v[160:161], off
	v_lshl_add_u64 v[160:161], s[36:37], 0, v[96:97]
	s_mov_b32 m0, s54
	s_nop 0
	global_load_lds_dwordx4 v[160:161], off
	v_lshl_add_u64 v[160:161], s[36:37], 0, v[130:131]
	s_add_i32 m0, s54, 0x2000
	s_nop 0
	global_load_lds_dwordx4 v[160:161], off
	v_lshl_add_u64 v[160:161], v[242:243], 0, s[38:39]
	s_mov_b32 m0, s31
	s_nop 0
	global_load_lds_dwordx4 v[160:161], off
	v_lshl_add_u64 v[160:161], v[244:245], 0, s[38:39]
	s_mov_b32 m0, s46
	s_nop 0
	global_load_lds_dwordx4 v[160:161], off
	s_waitcnt vmcnt(8)
	s_waitcnt lgkmcnt(0)
	v_mfma_f32_16x16x32_bf16 v[60:63], v[140:143], v[180:183], v[60:63]
	v_mfma_f32_16x16x32_bf16 v[52:55], v[152:155], v[180:183], v[52:55]
	v_mfma_f32_16x16x32_bf16 v[44:47], v[140:143], v[216:219], v[44:47]
	v_mfma_f32_16x16x32_bf16 v[36:39], v[152:155], v[216:219], v[36:39]
	s_barrier
	v_mfma_f32_16x16x32_bf16 v[28:31], v[140:143], v[224:227], v[28:31]
	v_mfma_f32_16x16x32_bf16 v[20:23], v[152:155], v[224:227], v[20:23]
	v_mfma_f32_16x16x32_bf16 v[12:15], v[140:143], v[232:235], v[12:15]
	v_mfma_f32_16x16x32_bf16 v[4:7], v[152:155], v[232:235], v[4:7]
	v_mfma_f32_16x16x32_bf16 v[60:63], v[148:151], v[184:187], v[60:63]
	v_mfma_f32_16x16x32_bf16 v[52:55], v[156:159], v[184:187], v[52:55]
	v_mfma_f32_16x16x32_bf16 v[44:47], v[148:151], v[220:223], v[44:47]
	v_mfma_f32_16x16x32_bf16 v[36:39], v[156:159], v[220:223], v[36:39]
	v_mfma_f32_16x16x32_bf16 v[28:31], v[148:151], v[228:231], v[28:31]
	v_mfma_f32_16x16x32_bf16 v[20:23], v[156:159], v[228:231], v[20:23]
	v_mfma_f32_16x16x32_bf16 v[12:15], v[148:151], v[236:239], v[12:15]
	v_mfma_f32_16x16x32_bf16 v[4:7], v[156:159], v[236:239], v[4:7]
	v_mfma_f32_16x16x32_bf16 v[56:59], v[164:167], v[180:183], v[56:59]
	v_mfma_f32_16x16x32_bf16 v[48:51], v[172:175], v[180:183], v[48:51]
	v_mfma_f32_16x16x32_bf16 v[40:43], v[164:167], v[216:219], v[40:43]
	v_mfma_f32_16x16x32_bf16 v[32:35], v[172:175], v[216:219], v[32:35]
	v_mfma_f32_16x16x32_bf16 v[24:27], v[164:167], v[224:227], v[24:27]
	v_mfma_f32_16x16x32_bf16 v[16:19], v[172:175], v[224:227], v[16:19]
	v_mfma_f32_16x16x32_bf16 v[8:11], v[164:167], v[232:235], v[8:11]
	v_mfma_f32_16x16x32_bf16 v[0:3], v[172:175], v[232:235], v[0:3]
	v_mfma_f32_16x16x32_bf16 v[56:59], v[168:171], v[184:187], v[56:59]
	v_mfma_f32_16x16x32_bf16 v[48:51], v[176:179], v[184:187], v[48:51]
	v_mfma_f32_16x16x32_bf16 v[40:43], v[168:171], v[220:223], v[40:43]
	v_mfma_f32_16x16x32_bf16 v[32:35], v[176:179], v[220:223], v[32:35]
	v_mfma_f32_16x16x32_bf16 v[24:27], v[168:171], v[228:231], v[24:27]
	v_mfma_f32_16x16x32_bf16 v[16:19], v[176:179], v[228:231], v[16:19]
	v_mfma_f32_16x16x32_bf16 v[8:11], v[168:171], v[236:239], v[8:11]
	v_mfma_f32_16x16x32_bf16 v[0:3], v[176:179], v[236:239], v[0:3]
	s_barrier
	s_add_i32 s53, s53, 2
	s_add_u32 s74, s74, 0x100
	s_addc_u32 s75, s75, 0
	s_add_u32 s47, s47, 0x100
	s_addc_u32 s51, s51, 0
	s_cmp_gt_u32 s53, 29
	s_cbranch_scc0 .LBB0_240
	s_and_b64 vcc, exec, s[24:25]
	s_cbranch_vccz .LBB0_243
	s_barrier

; #define PG8_STAGE(bufoff, gbase, voff) do { _Pragma("unroll") for (int _i = 0; _i < 2; ++_i) \
;         __builtin_amdgcn_global_load_lds((const unsigned*)((const char*)(gbase) + (voff)[_i]), (LAS unsigned*)(lds + (bufoff) + ldsw + _i * 8192), 16, 0, 0); } while (0)
; #define PG8_LDA(dst, b, h) do { _Pragma("unroll") for (int m = 0; m < 4; ++m) _Pragma("unroll") for (int k = 0; k < 2; ++k) dst[m][k] = *(const LAS bf16x8*)(lds + PG8_SA(b, h) + aoff + m * 2048 + k * 1024); } while (0)
; #define PG8_LDB(dst, b, h) do { _Pragma("unroll") for (int n = 0; n < 2; ++n) _Pragma("unroll") for (int k = 0; k < 2; ++k) dst[n][k] = *(const LAS bf16x8*)(lds + PG8_SB(b, h) + boff + n * 2048 + k * 1024); } while (0)
; #define PG8_MMA(ai, bj, At, Bt) do { __builtin_amdgcn_s_setprio(1); _Pragma("unroll") for (int m = 0; m < 4; ++m) _Pragma("unroll") for (int n = 0; n < 2; ++n) _Pragma("unroll") for (int k = 0; k < 2; ++k) \
;         acc[ai][bj][m][n] = __builtin_amdgcn_mfma_f32_16x16x32_bf16(Bt[n][k], At[m][k], acc[ai][bj][m][n], 0, 0, 0); __builtin_amdgcn_s_setprio(0); } while (0)
; #define PG8_WAIT_V(n) asm volatile("s_waitcnt vmcnt(" #n ")" ::: "memory")
; #define PG8_WAIT_L(n) asm volatile("s_waitcnt lgkmcnt(" #n ")" ::: "memory")
; #define PG8_BAR __builtin_amdgcn_s_barrier()
; #define PG8_SCHED __builtin_amdgcn_sched_barrier(0)
; template <class Epi, bool ALIGN_EPI, bool SP2, bool ROWHALF = false>
; DI void gemm_phase(LAS unsigned char* lds, const Gemm g, const StaticOrder& S, const Epi& E) {
;     ...
;             if constexpr (SP2) {
;             PG8_LDB(B0, 0, 0); PG8_LDB(B1, 0, 1); PG8_SCHED; PG8_LDA(At, 0, 0); PG8_STAGE(PG8_SA(1, 1), a1 + hA1, voffA);
;             PG8_WAIT_V(8); PG8_WAIT_L(0); PG8_BAR; PG8_MMA(0, 0, At, B0); PG8_MMA(0, 1, At, B1); PG8_BAR; PG8_SCHED;
;             if constexpr (!ROWHALF) { PG8_LDA(At, 0, 1); } PG8_STAGE(PG8_SB(0, 0), b2, voffB); PG8_STAGE(PG8_SB(0, 1), b2 + hstepB, voffB); PG8_STAGE(PG8_SA(0, 0), a2 + hA0, voffA);
;             PG8_WAIT_V(8); PG8_WAIT_L(0); PG8_BAR; if constexpr (!ROWHALF) { PG8_MMA(1, 0, At, B0); PG8_MMA(1, 1, At, B1); } PG8_BAR; PG8_SCHED;
.LBB0_251:
	s_add_u32 s22, s28, s18
	s_addc_u32 s23, s29, s19
	s_add_u32 s22, s22, 0x18080100
	s_addc_u32 s23, s23, 0
	s_add_u32 s36, s4, s18
	s_addc_u32 s37, s5, s19
	s_add_i32 s40, 0, 0x10000
	s_cmpk_eq_i32 s18, 0xf00
	s_cselect_b32 s41, s13, s23
	s_cselect_b32 s42, s7, s22
	s_cselect_b32 s23, s17, s37
	s_cselect_b32 s22, s16, s36
	s_add_i32 s43, 0, 0x14000
	v_add_u32_e32 v90, s40, v76
	v_add_u32_e32 v94, s43, v76
	ds_read_b128 v[78:81], v90
	ds_read_b128 v[82:85], v90 offset:1024
	ds_read_b128 v[86:89], v90 offset:2048
	ds_read_b128 v[90:93], v90 offset:3072
	ds_read_b128 v[98:101], v94
	ds_read_b128 v[102:105], v94 offset:1024
	ds_read_b128 v[106:109], v94 offset:2048
	ds_read_b128 v[110:113], v94 offset:3072
	v_lshl_add_u64 v[94:95], v[72:73], 0, s[18:19]
	s_add_i32 m0, s6, 0xc000
	ds_read_b128 v[114:117], v77
	ds_read_b128 v[118:121], v77 offset:1024
	ds_read_b128 v[122:125], v77 offset:2048
	ds_read_b128 v[126:129], v77 offset:3072
	ds_read_b128 v[130:133], v77 offset:4096
	ds_read_b128 v[134:137], v77 offset:5120
	ds_read_b128 v[138:141], v77 offset:6144
	ds_read_b128 v[142:145], v77 offset:7168
	global_load_lds_dwordx4 v[94:95], off
	v_lshl_add_u64 v[94:95], v[70:71], 0, s[18:19]
	s_add_i32 m0, s6, 0xe000
	s_nop 0
	global_load_lds_dwordx4 v[94:95], off
	s_waitcnt vmcnt(8)
	s_waitcnt lgkmcnt(0)
	v_mfma_f32_16x16x32_bf16 v[60:63], v[78:81], v[114:117], v[60:63]
	v_mfma_f32_16x16x32_bf16 v[52:55], v[86:89], v[114:117], v[52:55]
	v_mfma_f32_16x16x32_bf16 v[44:47], v[78:81], v[122:125], v[44:47]
	v_mfma_f32_16x16x32_bf16 v[36:39], v[86:89], v[122:125], v[36:39]
	s_barrier
	v_mfma_f32_16x16x32_bf16 v[28:31], v[78:81], v[130:133], v[28:31]
	v_mfma_f32_16x16x32_bf16 v[20:23], v[86:89], v[130:133], v[20:23]
	v_mfma_f32_16x16x32_bf16 v[12:15], v[78:81], v[138:141], v[12:15]
	v_mfma_f32_16x16x32_bf16 v[4:7], v[86:89], v[138:141], v[4:7]
	v_mfma_f32_16x16x32_bf16 v[60:63], v[82:85], v[118:121], v[60:63]
	v_mfma_f32_16x16x32_bf16 v[52:55], v[90:93], v[118:121], v[52:55]
	v_mfma_f32_16x16x32_bf16 v[44:47], v[82:85], v[126:129], v[44:47]
	v_mfma_f32_16x16x32_bf16 v[36:39], v[90:93], v[126:129], v[36:39]
	v_mfma_f32_16x16x32_bf16 v[28:31], v[82:85], v[134:137], v[28:31]
	v_mfma_f32_16x16x32_bf16 v[20:23], v[90:93], v[134:137], v[20:23]
	v_mfma_f32_16x16x32_bf16 v[12:15], v[82:85], v[142:145], v[12:15]
	v_mfma_f32_16x16x32_bf16 v[4:7], v[90:93], v[142:145], v[4:7]
	v_mfma_f32_16x16x32_bf16 v[56:59], v[98:101], v[114:117], v[56:59]
	v_mfma_f32_16x16x32_bf16 v[48:51], v[106:109], v[114:117], v[48:51]
	v_mfma_f32_16x16x32_bf16 v[40:43], v[98:101], v[122:125], v[40:43]
	v_mfma_f32_16x16x32_bf16 v[32:35], v[106:109], v[122:125], v[32:35]
	v_mfma_f32_16x16x32_bf16 v[24:27], v[98:101], v[130:133], v[24:27]
	v_mfma_f32_16x16x32_bf16 v[16:19], v[106:109], v[130:133], v[16:19]
	v_mfma_f32_16x16x32_bf16 v[8:11], v[98:101], v[138:141], v[8:11]
	v_mfma_f32_16x16x32_bf16 v[0:3], v[106:109], v[138:141], v[0:3]
	v_mfma_f32_16x16x32_bf16 v[56:59], v[102:105], v[118:121], v[56:59]
	v_mfma_f32_16x16x32_bf16 v[48:51], v[110:113], v[118:121], v[48:51]
	v_mfma_f32_16x16x32_bf16 v[40:43], v[102:105], v[126:129], v[40:43]
	v_mfma_f32_16x16x32_bf16 v[32:35], v[110:113], v[126:129], v[32:35]
	v_mfma_f32_16x16x32_bf16 v[24:27], v[102:105], v[134:137], v[24:27]
	v_mfma_f32_16x16x32_bf16 v[16:19], v[110:113], v[134:137], v[16:19]
	v_mfma_f32_16x16x32_bf16 v[8:11], v[102:105], v[142:145], v[8:11]
	v_mfma_f32_16x16x32_bf16 v[0:3], v[110:113], v[142:145], v[0:3]
	s_barrier
	s_add_i32 s36, s40, s12
	v_lshl_add_u64 v[94:95], s[22:23], 0, v[96:97]
	s_mov_b32 m0, s36
	v_lshl_add_u64 v[146:147], s[22:23], 0, v[68:69]
	global_load_lds_dwordx4 v[94:95], off
	s_add_i32 m0, s36, 0x2000
	s_add_u32 s36, s22, 0x80000
	s_addc_u32 s37, s23, 0
	s_add_i32 s40, s43, s12
	global_load_lds_dwordx4 v[146:147], off
	v_lshl_add_u64 v[78:79], s[36:37], 0, v[96:97]
	s_mov_b32 m0, s40
	s_nop 0
	global_load_lds_dwordx4 v[78:79], off
	s_add_i32 m0, s40, 0x2000
	v_lshl_add_u64 v[78:79], s[36:37], 0, v[68:69]
	s_add_u32 s36, s42, s3
	s_addc_u32 s37, s41, 0
	global_load_lds_dwordx4 v[78:79], off
	v_lshl_add_u64 v[148:149], s[36:37], 0, v[64:65]
	s_mov_b32 m0, s6
	v_lshl_add_u64 v[150:151], s[36:37], 0, v[66:67]
	global_load_lds_dwordx4 v[148:149], off
	s_mov_b32 m0, s20
	s_nop 0
	global_load_lds_dwordx4 v[150:151], off
	s_waitcnt vmcnt(8)
	s_waitcnt lgkmcnt(0)
	s_barrier
; #define PG8_STAGE(bufoff, gbase, voff) do { _Pragma("unroll") for (int _i = 0; _i < 2; ++_i) \
;         __builtin_amdgcn_global_load_lds((const unsigned*)((const char*)(gbase) + (voff)[_i]), (LAS unsigned*)(lds + (bufoff) + ldsw + _i * 8192), 16, 0, 0); } while (0)
; #define PG8_LDA(dst, b, h) do { _Pragma("unroll") for (int m = 0; m < 4; ++m) _Pragma("unroll") for (int k = 0; k < 2; ++k) dst[m][k] = *(const LAS bf16x8*)(lds + PG8_SA(b, h) + aoff + m * 2048 + k * 1024); } while (0)
; #define PG8_LDB(dst, b, h) do { _Pragma("unroll") for (int n = 0; n < 2; ++n) _Pragma("unroll") for (int k = 0; k < 2; ++k) dst[n][k] = *(const LAS bf16x8*)(lds + PG8_SB(b, h) + boff + n * 2048 + k * 1024); } while (0)
; #define PG8_MMA(ai, bj, At, Bt) do { __builtin_amdgcn_s_setprio(1); _Pragma("unroll") for (int m = 0; m < 4; ++m) _Pragma("unroll") for (int n = 0; n < 2; ++n) _Pragma("unroll") for (int k = 0; k < 2; ++k) \
;         acc[ai][bj][m][n] = __builtin_amdgcn_mfma_f32_16x16x32_bf16(Bt[n][k], At[m][k], acc[ai][bj][m][n], 0, 0, 0); __builtin_amdgcn_s_setprio(0); } while (0)
; #define PG8_WAIT_V(n) asm volatile("s_waitcnt vmcnt(" #n ")" ::: "memory")
; #define PG8_WAIT_L(n) asm volatile("s_waitcnt lgkmcnt(" #n ")" ::: "memory")
; #define PG8_BAR __builtin_amdgcn_s_barrier()
; #define PG8_SCHED __builtin_amdgcn_sched_barrier(0)
; template <class Epi, bool ALIGN_EPI, bool SP2, bool ROWHALF = false>
; DI void gemm_phase(LAS unsigned char* lds, const Gemm g, const StaticOrder& S, const Epi& E) {
;     ...
;             PG8_WAIT_V(8); PG8_WAIT_L(0); PG8_BAR; if constexpr (!ROWHALF) { PG8_MMA(1, 0, At, B0); PG8_MMA(1, 1, At, B1); } PG8_BAR; PG8_SCHED;
;             PG8_LDB(B0, 1, 0); PG8_LDB(B1, 1, 1); PG8_SCHED; PG8_LDA(At, 1, 0); PG8_STAGE(PG8_SA(0, 1), a2 + hA1, voffA);
;             PG8_WAIT_V(8); PG8_WAIT_L(0); PG8_BAR; PG8_MMA(0, 0, At, B0); PG8_MMA(0, 1, At, B1); PG8_BAR; PG8_SCHED;
;             if constexpr (!ROWHALF) { PG8_LDA(At, 1, 1); } PG8_STAGE(PG8_SB(1, 0), b3, voffB); PG8_STAGE(PG8_SB(1, 1), b3 + hstepB, voffB); PG8_STAGE(PG8_SA(1, 0), a3 + hA0, voffA);
;             PG8_WAIT_V(8); PG8_WAIT_L(0); PG8_BAR; if constexpr (!ROWHALF) { PG8_MMA(1, 0, At, B0); PG8_MMA(1, 1, At, B1); } PG8_BAR; PG8_SCHED;
	s_barrier
	s_add_i32 s40, 0, 0x18000
	s_add_i32 s43, 0, 0x1c000
	v_add_u32_e32 v90, s40, v76
	v_add_u32_e32 v110, s43, v76
	ds_read_b128 v[78:81], v90
	ds_read_b128 v[82:85], v90 offset:1024
	ds_read_b128 v[86:89], v90 offset:2048
	ds_read_b128 v[90:93], v90 offset:3072
	ds_read_b128 v[98:101], v110
	ds_read_b128 v[102:105], v110 offset:1024
	ds_read_b128 v[106:109], v110 offset:2048
	ds_read_b128 v[110:113], v110 offset:3072
	s_add_u32 s36, s42, s8
	s_addc_u32 s37, s41, 0
	s_mov_b32 m0, s21
	v_lshl_add_u64 v[152:153], s[36:37], 0, v[64:65]
	ds_read_b128 v[114:117], v77 offset:32768
	ds_read_b128 v[118:121], v77 offset:33792
	ds_read_b128 v[122:125], v77 offset:34816
	ds_read_b128 v[126:129], v77 offset:35840
	ds_read_b128 v[130:133], v77 offset:36864
	ds_read_b128 v[134:137], v77 offset:37888
	ds_read_b128 v[138:141], v77 offset:38912
	ds_read_b128 v[142:145], v77 offset:39936
	global_load_lds_dwordx4 v[152:153], off
	v_lshl_add_u64 v[152:153], s[36:37], 0, v[66:67]
	s_mov_b32 m0, s24
	s_nop 0
	global_load_lds_dwordx4 v[152:153], off
	s_waitcnt vmcnt(8)
	s_waitcnt lgkmcnt(0)
	v_mfma_f32_16x16x32_bf16 v[60:63], v[78:81], v[114:117], v[60:63]
	v_mfma_f32_16x16x32_bf16 v[52:55], v[86:89], v[114:117], v[52:55]
	v_mfma_f32_16x16x32_bf16 v[44:47], v[78:81], v[122:125], v[44:47]
	v_mfma_f32_16x16x32_bf16 v[36:39], v[86:89], v[122:125], v[36:39]
	s_barrier
	v_mfma_f32_16x16x32_bf16 v[28:31], v[78:81], v[130:133], v[28:31]
	v_mfma_f32_16x16x32_bf16 v[20:23], v[86:89], v[130:133], v[20:23]
	v_mfma_f32_16x16x32_bf16 v[12:15], v[78:81], v[138:141], v[12:15]
	v_mfma_f32_16x16x32_bf16 v[4:7], v[86:89], v[138:141], v[4:7]
	v_mfma_f32_16x16x32_bf16 v[60:63], v[82:85], v[118:121], v[60:63]
	v_mfma_f32_16x16x32_bf16 v[52:55], v[90:93], v[118:121], v[52:55]
	v_mfma_f32_16x16x32_bf16 v[44:47], v[82:85], v[126:129], v[44:47]
	v_mfma_f32_16x16x32_bf16 v[36:39], v[90:93], v[126:129], v[36:39]
	v_mfma_f32_16x16x32_bf16 v[28:31], v[82:85], v[134:137], v[28:31]
	v_mfma_f32_16x16x32_bf16 v[20:23], v[90:93], v[134:137], v[20:23]
	v_mfma_f32_16x16x32_bf16 v[12:15], v[82:85], v[142:145], v[12:15]
	v_mfma_f32_16x16x32_bf16 v[4:7], v[90:93], v[142:145], v[4:7]
	v_mfma_f32_16x16x32_bf16 v[56:59], v[98:101], v[114:117], v[56:59]
	v_mfma_f32_16x16x32_bf16 v[48:51], v[106:109], v[114:117], v[48:51]
	v_mfma_f32_16x16x32_bf16 v[40:43], v[98:101], v[122:125], v[40:43]
	v_mfma_f32_16x16x32_bf16 v[32:35], v[106:109], v[122:125], v[32:35]
	v_mfma_f32_16x16x32_bf16 v[24:27], v[98:101], v[130:133], v[24:27]
	v_mfma_f32_16x16x32_bf16 v[16:19], v[106:109], v[130:133], v[16:19]
	v_mfma_f32_16x16x32_bf16 v[8:11], v[98:101], v[138:141], v[8:11]
	v_mfma_f32_16x16x32_bf16 v[0:3], v[106:109], v[138:141], v[0:3]
	v_mfma_f32_16x16x32_bf16 v[56:59], v[102:105], v[118:121], v[56:59]
	v_mfma_f32_16x16x32_bf16 v[48:51], v[110:113], v[118:121], v[48:51]
	v_mfma_f32_16x16x32_bf16 v[40:43], v[102:105], v[126:129], v[40:43]
	v_mfma_f32_16x16x32_bf16 v[32:35], v[110:113], v[126:129], v[32:35]
	v_mfma_f32_16x16x32_bf16 v[24:27], v[102:105], v[134:137], v[24:27]
	v_mfma_f32_16x16x32_bf16 v[16:19], v[110:113], v[134:137], v[16:19]
	v_mfma_f32_16x16x32_bf16 v[8:11], v[102:105], v[142:145], v[8:11]
	v_mfma_f32_16x16x32_bf16 v[0:3], v[110:113], v[142:145], v[0:3]
	s_barrier
	s_add_i32 s36, s40, s12
	v_lshl_add_u64 v[78:79], v[94:95], 0, s[38:39]
	s_mov_b32 m0, s36
	s_nop 0
	global_load_lds_dwordx4 v[78:79], off
	s_add_i32 m0, s36, 0x2000
	s_add_u32 s22, s22, 0x80080
	v_lshl_add_u64 v[78:79], v[146:147], 0, s[38:39]
	s_addc_u32 s23, s23, 0
	s_add_i32 s36, s43, s12
	global_load_lds_dwordx4 v[78:79], off
	v_lshl_add_u64 v[78:79], s[22:23], 0, v[96:97]
	s_mov_b32 m0, s36
	s_nop 0
	global_load_lds_dwordx4 v[78:79], off
	v_lshl_add_u64 v[78:79], s[22:23], 0, v[68:69]
	s_add_i32 m0, s36, 0x2000
	s_nop 0
	global_load_lds_dwordx4 v[78:79], off
	v_lshl_add_u64 v[78:79], v[148:149], 0, s[38:39]
	s_mov_b32 m0, s26
	s_nop 0
	global_load_lds_dwordx4 v[78:79], off
	v_lshl_add_u64 v[78:79], v[150:151], 0, s[38:39]
	s_mov_b32 m0, s27
	s_nop 0
	global_load_lds_dwordx4 v[78:79], off
	s_waitcnt vmcnt(8)
	s_waitcnt lgkmcnt(0)
	s_barrier
	s_barrier
	s_add_i32 s31, s31, 2
	s_add_u32 s18, s18, 0x100
	s_addc_u32 s19, s19, 0
	s_cmp_gt_u32 s31, 29
	s_cbranch_scc0 .LBB0_251
	s_cmpk_lt_u32 s9, 0x100
	s_cbranch_scc0 .LBB0_254
	s_barrier
